# v25 (all attention + rope/rpb/epilogue edits + finalize gate prefetch + max tree) + non-temporal hint on in-proj Z stores
# speedup vs baseline: 1.0247x; 1.0026x over previous
.LBB0_145:
	v_pk_mul_f32 v[174:175], v[126:127], v[164:165]
	v_lshl_or_b32 v158, s55, 8, v168
	v_sub_f32_e32 v0, v174, v175
	v_mov_b32_e32 v174, v165
	v_mov_b32_e32 v175, v164
	v_pk_mul_f32 v[126:127], v[126:127], v[174:175]
	v_mov_b64_e32 v[172:173], s[12:13]
	v_add_f32_e32 v171, v126, v127
	v_pk_mul_f32 v[126:127], v[128:129], v[130:131]
	v_mov_b32_e32 v176, v133
	v_sub_f32_e32 v178, v126, v127
	v_mov_b32_e32 v126, v131
	v_mov_b32_e32 v127, v130
	v_pk_mul_f32 v[128:129], v[128:129], v[126:127]
	v_mov_b32_e32 v177, v132
	v_add_f32_e32 v179, v128, v129
	v_pk_mul_f32 v[128:129], v[122:123], v[162:163]
	v_ashrrev_i32_e32 v159, 31, v158
	v_sub_f32_e32 v180, v128, v129
	v_mov_b32_e32 v128, v163
	v_mov_b32_e32 v129, v162
	v_pk_mul_f32 v[122:123], v[122:123], v[128:129]
	v_mad_i64_i32 v[172:173], s[0:1], v170, s43, v[172:173]
	v_add_f32_e32 v181, v122, v123
	v_pk_mul_f32 v[122:123], v[124:125], v[132:133]
	v_lshl_add_u64 v[172:173], v[158:159], 1, v[172:173]
	v_sub_f32_e32 v182, v122, v123
	v_pk_mul_f32 v[122:123], v[124:125], v[176:177]
	s_nop 0
	v_add_f32_e32 v125, v122, v123
	v_cvt_pk_bf16_f32 v122, v0, v171
	v_cvt_pk_bf16_f32 v123, v178, v179
	v_cvt_pk_bf16_f32 v124, v180, v181
	v_cvt_pk_bf16_f32 v125, v182, v125
	global_store_dwordx4 v[172:173], v[122:125], off nt
	s_nop 1
	v_pk_mul_f32 v[122:123], v[118:119], v[164:165]
	v_pk_mul_f32 v[118:119], v[118:119], v[174:175]
	v_sub_f32_e32 v0, v122, v123
	v_add_f32_e32 v122, v118, v119
	v_pk_mul_f32 v[118:119], v[120:121], v[130:131]
	s_nop 0
	v_sub_f32_e32 v123, v118, v119
	v_pk_mul_f32 v[118:119], v[120:121], v[126:127]
	s_nop 0
	v_add_f32_e32 v120, v118, v119
	v_pk_mul_f32 v[118:119], v[114:115], v[162:163]
	v_pk_mul_f32 v[114:115], v[114:115], v[128:129]
	v_sub_f32_e32 v118, v118, v119
	v_add_f32_e32 v119, v114, v115
	v_pk_mul_f32 v[114:115], v[116:117], v[132:133]
	s_nop 0
	v_sub_f32_e32 v121, v114, v115
	v_pk_mul_f32 v[114:115], v[116:117], v[176:177]
	s_nop 0
	v_add_f32_e32 v117, v114, v115
	v_cvt_pk_bf16_f32 v114, v0, v122
	v_cvt_pk_bf16_f32 v115, v123, v120
	v_cvt_pk_bf16_f32 v116, v118, v119
	v_cvt_pk_bf16_f32 v117, v121, v117
	global_store_dwordx4 v[172:173], v[114:117], off offset:256 nt
	v_cndmask_b32_e64 v0, 0, 1, s[10:11]
	v_or_b32_e32 v120, 16, v170
	v_cmp_ne_u32_e64 s[8:9], 1, v0
	s_andn2_b64 vcc, exec, s[10:11]
	v_mov_b32_e32 v115, 0
	v_mov_b32_e32 v119, 0
	v_mov_b32_e32 v117, 0
	v_mov_b32_e32 v114, 1.0
	v_mov_b32_e32 v118, 1.0
	v_mov_b32_e32 v116, 1.0
	s_cbranch_vccnz .LBB0_147
	s_waitcnt vmcnt(10)
	v_mov_b32_e32 v114, v192
	v_mov_b32_e32 v115, v193
	v_mov_b32_e32 v116, v194
	v_mov_b32_e32 v117, v195
	v_mov_b32_e32 v122, v196
	v_mov_b32_e32 v123, v197
	v_mov_b32_e32 v124, v198
	v_mov_b32_e32 v125, v199
	v_mov_b32_e32 v161, v114
	v_mov_b32_e32 v119, v116
	v_mov_b32_e32 v160, v122
	v_mov_b32_e32 v114, v123
	v_mov_b32_e32 v118, v124
	v_mov_b32_e32 v116, v125
.LBB0_147:
	v_mov_b64_e32 v[122:123], s[12:13]
	v_mad_i64_i32 v[120:121], s[0:1], v120, s43, v[122:123]
	v_pk_mul_f32 v[122:123], v[110:111], v[160:161]
	v_mov_b32_e32 v124, v117
	v_sub_f32_e32 v0, v122, v123
	v_mov_b32_e32 v122, v161
	v_mov_b32_e32 v123, v160
	v_pk_mul_f32 v[110:111], v[110:111], v[122:123]
	v_mov_b32_e32 v125, v116
	v_add_f32_e32 v126, v110, v111
	v_pk_mul_f32 v[110:111], v[112:113], v[114:115]
	v_lshl_add_u64 v[120:121], v[158:159], 1, v[120:121]
	v_sub_f32_e32 v127, v110, v111
	v_mov_b32_e32 v110, v115
	v_mov_b32_e32 v111, v114
	v_pk_mul_f32 v[112:113], v[112:113], v[110:111]
	s_nop 0
	v_add_f32_e32 v128, v112, v113
	v_pk_mul_f32 v[112:113], v[106:107], v[118:119]
	s_nop 0
	v_sub_f32_e32 v129, v112, v113
	v_mov_b32_e32 v112, v119
	v_mov_b32_e32 v113, v118
	v_pk_mul_f32 v[106:107], v[106:107], v[112:113]
	s_nop 0
	v_add_f32_e32 v130, v106, v107
	v_pk_mul_f32 v[106:107], v[108:109], v[116:117]
	s_nop 0
	v_sub_f32_e32 v131, v106, v107
	v_pk_mul_f32 v[106:107], v[108:109], v[124:125]
	s_nop 0
	v_add_f32_e32 v109, v106, v107
	v_cvt_pk_bf16_f32 v106, v0, v126
	v_cvt_pk_bf16_f32 v107, v127, v128
	v_cvt_pk_bf16_f32 v108, v129, v130
	v_cvt_pk_bf16_f32 v109, v131, v109
	global_store_dwordx4 v[120:121], v[106:109], off nt
	s_nop 1
	v_pk_mul_f32 v[106:107], v[102:103], v[160:161]
	v_pk_mul_f32 v[102:103], v[102:103], v[122:123]
	v_sub_f32_e32 v0, v106, v107
	v_add_f32_e32 v106, v102, v103
	v_pk_mul_f32 v[102:103], v[104:105], v[114:115]
	s_nop 0
	v_sub_f32_e32 v107, v102, v103
	v_pk_mul_f32 v[102:103], v[104:105], v[110:111]
	s_nop 0
	v_add_f32_e32 v104, v102, v103
	v_pk_mul_f32 v[102:103], v[98:99], v[118:119]
	v_pk_mul_f32 v[98:99], v[98:99], v[112:113]
	v_sub_f32_e32 v102, v102, v103
	v_add_f32_e32 v103, v98, v99
	v_pk_mul_f32 v[98:99], v[100:101], v[116:117]
	s_nop 0
	v_sub_f32_e32 v105, v98, v99
	v_pk_mul_f32 v[98:99], v[100:101], v[124:125]
	s_nop 0
	v_add_f32_e32 v101, v98, v99
	v_cvt_pk_bf16_f32 v98, v0, v106
	v_cvt_pk_bf16_f32 v99, v107, v104
	v_cvt_pk_bf16_f32 v100, v102, v103
	v_cvt_pk_bf16_f32 v101, v105, v101
	global_store_dwordx4 v[120:121], v[98:101], off offset:256 nt
	v_or_b32_e32 v108, 32, v170
	v_mov_b32_e32 v102, 1.0
	v_mov_b32_e32 v103, 0
	s_and_b64 vcc, exec, s[8:9]
	v_mov_b32_e32 v107, 0
	v_mov_b32_e32 v99, 0
	v_mov_b32_e32 v105, 0
	v_mov_b32_e32 v101, 0
	v_mov_b32_e32 v106, 1.0
	v_mov_b32_e32 v98, 1.0
	v_mov_b32_e32 v104, 1.0
	v_mov_b32_e32 v100, 1.0
	s_cbranch_vccnz .LBB0_149
	v_add_u32_e32 v244, 0xa0, v170
	v_lshlrev_b32_e32 v244, 8, v244
	v_and_b32_e32 v244, 0x7ff00, v244
	v_lshl_add_u64 v[246:247], v[142:143], 0, v[244:245]
	global_load_dwordx4 v[184:187], v[246:247], off
	v_lshl_add_u64 v[246:247], v[144:145], 0, v[244:245]
	global_load_dwordx4 v[188:191], v[246:247], off
	v_add_u32_e32 v244, 0xb0, v170
	v_lshlrev_b32_e32 v244, 8, v244
	v_and_b32_e32 v244, 0x7ff00, v244
	v_lshl_add_u64 v[246:247], v[142:143], 0, v[244:245]
	global_load_dwordx4 v[192:195], v[246:247], off
	v_lshl_add_u64 v[246:247], v[144:145], 0, v[244:245]
	global_load_dwordx4 v[196:199], v[246:247], off
	s_waitcnt vmcnt(14)
	v_mov_b32_e32 v98, v200
	v_mov_b32_e32 v99, v201
	v_mov_b32_e32 v100, v202
	v_mov_b32_e32 v101, v203
	v_mov_b32_e32 v110, v216
	v_mov_b32_e32 v111, v217
	v_mov_b32_e32 v112, v218
	v_mov_b32_e32 v113, v219
	v_mov_b32_e32 v107, v98
	v_mov_b32_e32 v105, v100
	v_mov_b32_e32 v106, v110
	v_mov_b32_e32 v98, v111
	v_mov_b32_e32 v104, v112
	v_mov_b32_e32 v100, v113
.LBB0_149:
	v_mov_b64_e32 v[110:111], s[12:13]
	v_mad_i64_i32 v[108:109], s[0:1], v108, s43, v[110:111]
	v_pk_mul_f32 v[110:111], v[94:95], v[106:107]
	v_mov_b32_e32 v112, v101
	v_sub_f32_e32 v0, v110, v111
	v_mov_b32_e32 v110, v107
	v_mov_b32_e32 v111, v106
	v_pk_mul_f32 v[94:95], v[94:95], v[110:111]
	v_mov_b32_e32 v113, v100
	v_add_f32_e32 v114, v94, v95
	v_pk_mul_f32 v[94:95], v[96:97], v[98:99]
	v_lshl_add_u64 v[108:109], v[158:159], 1, v[108:109]
	v_sub_f32_e32 v115, v94, v95
	v_mov_b32_e32 v94, v99
	v_mov_b32_e32 v95, v98
	v_pk_mul_f32 v[96:97], v[96:97], v[94:95]
	s_nop 0
	v_add_f32_e32 v116, v96, v97
	v_pk_mul_f32 v[96:97], v[90:91], v[104:105]
	s_nop 0
	v_sub_f32_e32 v117, v96, v97
	v_mov_b32_e32 v96, v105
	v_mov_b32_e32 v97, v104
	v_pk_mul_f32 v[90:91], v[90:91], v[96:97]
	s_nop 0
	v_add_f32_e32 v118, v90, v91
	v_pk_mul_f32 v[90:91], v[92:93], v[100:101]
	s_nop 0
	v_sub_f32_e32 v119, v90, v91
	v_pk_mul_f32 v[90:91], v[92:93], v[112:113]
	s_nop 0
	v_add_f32_e32 v93, v90, v91
	v_cvt_pk_bf16_f32 v90, v0, v114
	v_cvt_pk_bf16_f32 v91, v115, v116
	v_cvt_pk_bf16_f32 v92, v117, v118
	v_cvt_pk_bf16_f32 v93, v119, v93
	global_store_dwordx4 v[108:109], v[90:93], off nt
	s_nop 1
	v_pk_mul_f32 v[90:91], v[86:87], v[106:107]
	v_pk_mul_f32 v[86:87], v[86:87], v[110:111]
	v_sub_f32_e32 v0, v90, v91
	v_add_f32_e32 v90, v86, v87
	v_pk_mul_f32 v[86:87], v[88:89], v[98:99]
	s_nop 0
	v_sub_f32_e32 v91, v86, v87
	v_pk_mul_f32 v[86:87], v[88:89], v[94:95]
	s_nop 0
	v_add_f32_e32 v88, v86, v87
	v_pk_mul_f32 v[86:87], v[82:83], v[104:105]
	v_pk_mul_f32 v[82:83], v[82:83], v[96:97]
	v_sub_f32_e32 v86, v86, v87
	v_add_f32_e32 v87, v82, v83
	v_pk_mul_f32 v[82:83], v[84:85], v[100:101]
	s_nop 0
	v_sub_f32_e32 v89, v82, v83
	v_pk_mul_f32 v[82:83], v[84:85], v[112:113]
	s_nop 0
	v_add_f32_e32 v85, v82, v83
	v_cvt_pk_bf16_f32 v82, v0, v90
	v_cvt_pk_bf16_f32 v83, v91, v88
	v_cvt_pk_bf16_f32 v84, v86, v87
	v_cvt_pk_bf16_f32 v85, v89, v85
	global_store_dwordx4 v[108:109], v[82:85], off offset:256 nt
	v_or_b32_e32 v88, 48, v170
	s_and_b64 vcc, exec, s[8:9]
	v_mov_b32_e32 v83, 0
	v_mov_b32_e32 v87, 0
	v_mov_b32_e32 v85, 0
	v_mov_b32_e32 v82, 1.0
	v_mov_b32_e32 v86, 1.0
	v_mov_b32_e32 v84, 1.0
	s_cbranch_vccnz .LBB0_151
	s_waitcnt vmcnt(14)
	v_mov_b32_e32 v82, v220
	v_mov_b32_e32 v83, v221
	v_mov_b32_e32 v84, v222
	v_mov_b32_e32 v85, v223
	v_mov_b32_e32 v90, v224
	v_mov_b32_e32 v91, v225
	v_mov_b32_e32 v92, v226
	v_mov_b32_e32 v93, v227
	v_mov_b32_e32 v103, v82
	v_mov_b32_e32 v87, v84
	v_mov_b32_e32 v102, v90
	v_mov_b32_e32 v82, v91
	v_mov_b32_e32 v86, v92
	v_mov_b32_e32 v84, v93
.LBB0_151:
	v_mov_b64_e32 v[90:91], s[12:13]
	v_mad_i64_i32 v[88:89], s[0:1], v88, s43, v[90:91]
	v_pk_mul_f32 v[90:91], v[78:79], v[102:103]
	v_mov_b32_e32 v92, v85
	v_sub_f32_e32 v0, v90, v91
	v_mov_b32_e32 v90, v103
	v_mov_b32_e32 v91, v102
	v_pk_mul_f32 v[78:79], v[78:79], v[90:91]
	v_mov_b32_e32 v93, v84
	v_add_f32_e32 v94, v78, v79
	v_pk_mul_f32 v[78:79], v[80:81], v[82:83]
	v_lshl_add_u64 v[88:89], v[158:159], 1, v[88:89]
	v_sub_f32_e32 v95, v78, v79
	v_mov_b32_e32 v78, v83
	v_mov_b32_e32 v79, v82
	v_pk_mul_f32 v[80:81], v[80:81], v[78:79]
	s_nop 0
	v_add_f32_e32 v96, v80, v81
	v_pk_mul_f32 v[80:81], v[74:75], v[86:87]
	s_nop 0
	v_sub_f32_e32 v97, v80, v81
	v_mov_b32_e32 v80, v87
	v_mov_b32_e32 v81, v86
	v_pk_mul_f32 v[74:75], v[74:75], v[80:81]
	s_nop 0
	v_add_f32_e32 v98, v74, v75
	v_pk_mul_f32 v[74:75], v[76:77], v[84:85]
	s_nop 0
	v_sub_f32_e32 v99, v74, v75
	v_pk_mul_f32 v[74:75], v[76:77], v[92:93]
	s_nop 0
	v_add_f32_e32 v77, v74, v75
	v_cvt_pk_bf16_f32 v74, v0, v94
	v_cvt_pk_bf16_f32 v75, v95, v96
	v_cvt_pk_bf16_f32 v76, v97, v98
	v_cvt_pk_bf16_f32 v77, v99, v77
	global_store_dwordx4 v[88:89], v[74:77], off nt
	s_nop 1
	v_pk_mul_f32 v[74:75], v[70:71], v[102:103]
	v_pk_mul_f32 v[70:71], v[70:71], v[90:91]
	v_sub_f32_e32 v0, v74, v75
	v_add_f32_e32 v74, v70, v71
	v_pk_mul_f32 v[70:71], v[72:73], v[82:83]
	s_nop 0
	v_sub_f32_e32 v75, v70, v71
	v_pk_mul_f32 v[70:71], v[72:73], v[78:79]
	s_nop 0
	v_add_f32_e32 v72, v70, v71
	v_pk_mul_f32 v[70:71], v[66:67], v[86:87]
	v_pk_mul_f32 v[66:67], v[66:67], v[80:81]
	v_sub_f32_e32 v70, v70, v71
	v_add_f32_e32 v71, v66, v67
	v_pk_mul_f32 v[66:67], v[68:69], v[84:85]
	s_nop 0
	v_sub_f32_e32 v73, v66, v67
	v_pk_mul_f32 v[66:67], v[68:69], v[92:93]
	s_nop 0
	v_add_f32_e32 v69, v66, v67
	v_cvt_pk_bf16_f32 v66, v0, v74
	v_cvt_pk_bf16_f32 v67, v75, v72
	v_cvt_pk_bf16_f32 v68, v70, v71
	v_cvt_pk_bf16_f32 v69, v73, v69
	global_store_dwordx4 v[88:89], v[66:69], off offset:256 nt
	v_add_u32_e32 v76, 0x80, v170
	v_mov_b32_e32 v70, 1.0
	v_mov_b32_e32 v71, 0
	s_and_b64 vcc, exec, s[8:9]
	v_mov_b32_e32 v75, 0
	v_mov_b32_e32 v67, 0
	v_mov_b32_e32 v73, 0
	v_mov_b32_e32 v69, 0
	v_mov_b32_e32 v74, 1.0
	v_mov_b32_e32 v66, 1.0
	v_mov_b32_e32 v72, 1.0
	v_mov_b32_e32 v68, 1.0
	s_cbranch_vccnz .LBB0_153
	s_waitcnt vmcnt(14)
	v_mov_b32_e32 v66, v228
	v_mov_b32_e32 v67, v229
	v_mov_b32_e32 v68, v230
	v_mov_b32_e32 v69, v231
	v_mov_b32_e32 v78, v232
	v_mov_b32_e32 v79, v233
	v_mov_b32_e32 v80, v234
	v_mov_b32_e32 v81, v235
	v_mov_b32_e32 v75, v66
	v_mov_b32_e32 v73, v68
	v_mov_b32_e32 v74, v78
	v_mov_b32_e32 v66, v79
	v_mov_b32_e32 v72, v80
	v_mov_b32_e32 v68, v81
.LBB0_153:
	v_mov_b64_e32 v[78:79], s[12:13]
	v_mad_i64_i32 v[76:77], s[0:1], v76, s43, v[78:79]
	v_pk_mul_f32 v[78:79], v[62:63], v[74:75]
	v_mov_b32_e32 v80, v69
	v_sub_f32_e32 v0, v78, v79
	v_mov_b32_e32 v78, v75
	v_mov_b32_e32 v79, v74
	v_pk_mul_f32 v[62:63], v[62:63], v[78:79]
	v_mov_b32_e32 v81, v68
	v_add_f32_e32 v82, v62, v63
	v_pk_mul_f32 v[62:63], v[64:65], v[66:67]
	v_lshl_add_u64 v[76:77], v[158:159], 1, v[76:77]
	v_sub_f32_e32 v83, v62, v63
	v_mov_b32_e32 v62, v67
	v_mov_b32_e32 v63, v66
	v_pk_mul_f32 v[64:65], v[64:65], v[62:63]
	s_nop 0
	v_add_f32_e32 v84, v64, v65
	v_pk_mul_f32 v[64:65], v[58:59], v[72:73]
	s_nop 0
	v_sub_f32_e32 v85, v64, v65
	v_mov_b32_e32 v64, v73
	v_mov_b32_e32 v65, v72
	v_pk_mul_f32 v[58:59], v[58:59], v[64:65]
	s_nop 0
	v_add_f32_e32 v86, v58, v59
	v_pk_mul_f32 v[58:59], v[60:61], v[68:69]
	s_nop 0
	v_sub_f32_e32 v87, v58, v59
	v_pk_mul_f32 v[58:59], v[60:61], v[80:81]
	s_nop 0
	v_add_f32_e32 v61, v58, v59
	v_cvt_pk_bf16_f32 v58, v0, v82
	v_cvt_pk_bf16_f32 v59, v83, v84
	v_cvt_pk_bf16_f32 v60, v85, v86
	v_cvt_pk_bf16_f32 v61, v87, v61
	global_store_dwordx4 v[76:77], v[58:61], off nt
	s_nop 1
	v_pk_mul_f32 v[58:59], v[54:55], v[74:75]
	v_pk_mul_f32 v[54:55], v[54:55], v[78:79]
	v_sub_f32_e32 v0, v58, v59
	v_add_f32_e32 v58, v54, v55
	v_pk_mul_f32 v[54:55], v[56:57], v[66:67]
	s_nop 0
	v_sub_f32_e32 v59, v54, v55
	v_pk_mul_f32 v[54:55], v[56:57], v[62:63]
	s_nop 0
	v_add_f32_e32 v56, v54, v55
	v_pk_mul_f32 v[54:55], v[50:51], v[72:73]
	v_pk_mul_f32 v[50:51], v[50:51], v[64:65]
	v_sub_f32_e32 v54, v54, v55
	v_add_f32_e32 v55, v50, v51
	v_pk_mul_f32 v[50:51], v[52:53], v[68:69]
	s_nop 0
	v_sub_f32_e32 v57, v50, v51
	v_pk_mul_f32 v[50:51], v[52:53], v[80:81]
	s_nop 0
	v_add_f32_e32 v53, v50, v51
	v_cvt_pk_bf16_f32 v50, v0, v58
	v_cvt_pk_bf16_f32 v51, v59, v56
	v_cvt_pk_bf16_f32 v52, v54, v55
	v_cvt_pk_bf16_f32 v53, v57, v53
	global_store_dwordx4 v[76:77], v[50:53], off offset:256 nt
	v_add_u32_e32 v56, 0x90, v170
	s_and_b64 vcc, exec, s[8:9]
	v_mov_b32_e32 v51, 0
	v_mov_b32_e32 v55, 0
	v_mov_b32_e32 v53, 0
	v_mov_b32_e32 v50, 1.0
	v_mov_b32_e32 v54, 1.0
	v_mov_b32_e32 v52, 1.0
	s_cbranch_vccnz .LBB0_155
	s_waitcnt vmcnt(14)
	v_mov_b32_e32 v50, v236
	v_mov_b32_e32 v51, v237
	v_mov_b32_e32 v52, v238
	v_mov_b32_e32 v53, v239
	v_mov_b32_e32 v58, v240
	v_mov_b32_e32 v59, v241
	v_mov_b32_e32 v60, v242
	v_mov_b32_e32 v61, v243
	v_mov_b32_e32 v71, v50
	v_mov_b32_e32 v55, v52
	v_mov_b32_e32 v70, v58
	v_mov_b32_e32 v50, v59
	v_mov_b32_e32 v54, v60
	v_mov_b32_e32 v52, v61
.LBB0_155:
	v_mov_b64_e32 v[58:59], s[12:13]
	v_mad_i64_i32 v[56:57], s[0:1], v56, s43, v[58:59]
	v_pk_mul_f32 v[58:59], v[46:47], v[70:71]
	v_mov_b32_e32 v60, v53
	v_sub_f32_e32 v0, v58, v59
	v_mov_b32_e32 v58, v71
	v_mov_b32_e32 v59, v70
	v_pk_mul_f32 v[46:47], v[46:47], v[58:59]
	v_mov_b32_e32 v61, v52
	v_add_f32_e32 v62, v46, v47
	v_pk_mul_f32 v[46:47], v[48:49], v[50:51]
	v_lshl_add_u64 v[56:57], v[158:159], 1, v[56:57]
	v_sub_f32_e32 v63, v46, v47
	v_mov_b32_e32 v46, v51
	v_mov_b32_e32 v47, v50
	v_pk_mul_f32 v[48:49], v[48:49], v[46:47]
	s_nop 0
	v_add_f32_e32 v64, v48, v49
	v_pk_mul_f32 v[48:49], v[42:43], v[54:55]
	s_nop 0
	v_sub_f32_e32 v65, v48, v49
	v_mov_b32_e32 v48, v55
	v_mov_b32_e32 v49, v54
	v_pk_mul_f32 v[42:43], v[42:43], v[48:49]
	s_nop 0
	v_add_f32_e32 v66, v42, v43
	v_pk_mul_f32 v[42:43], v[44:45], v[52:53]
	s_nop 0
	v_sub_f32_e32 v67, v42, v43
	v_pk_mul_f32 v[42:43], v[44:45], v[60:61]
	s_nop 0
	v_add_f32_e32 v45, v42, v43
	v_cvt_pk_bf16_f32 v42, v0, v62
	v_cvt_pk_bf16_f32 v43, v63, v64
	v_cvt_pk_bf16_f32 v44, v65, v66
	v_cvt_pk_bf16_f32 v45, v67, v45
	global_store_dwordx4 v[56:57], v[42:45], off nt
	s_nop 1
	v_pk_mul_f32 v[42:43], v[38:39], v[70:71]
	v_pk_mul_f32 v[38:39], v[38:39], v[58:59]
	v_sub_f32_e32 v0, v42, v43
	v_add_f32_e32 v42, v38, v39
	v_pk_mul_f32 v[38:39], v[40:41], v[50:51]
	s_nop 0
	v_sub_f32_e32 v43, v38, v39
	v_pk_mul_f32 v[38:39], v[40:41], v[46:47]
	s_nop 0
	v_add_f32_e32 v40, v38, v39
	v_pk_mul_f32 v[38:39], v[34:35], v[54:55]
	v_pk_mul_f32 v[34:35], v[34:35], v[48:49]
	v_sub_f32_e32 v38, v38, v39
	v_add_f32_e32 v39, v34, v35
	v_pk_mul_f32 v[34:35], v[36:37], v[52:53]
	s_nop 0
	v_sub_f32_e32 v41, v34, v35
	v_pk_mul_f32 v[34:35], v[36:37], v[60:61]
	s_nop 0
	v_add_f32_e32 v37, v34, v35
	v_cvt_pk_bf16_f32 v34, v0, v42
	v_cvt_pk_bf16_f32 v35, v43, v40
	v_cvt_pk_bf16_f32 v36, v38, v39
	v_cvt_pk_bf16_f32 v37, v41, v37
	global_store_dwordx4 v[56:57], v[34:37], off offset:256 nt
	v_add_u32_e32 v44, 0xa0, v170
	v_mov_b32_e32 v38, 1.0
	v_mov_b32_e32 v39, 0
	s_and_b64 vcc, exec, s[8:9]
	v_mov_b32_e32 v43, 0
	v_mov_b32_e32 v35, 0
	v_mov_b32_e32 v41, 0
	v_mov_b32_e32 v37, 0
	v_mov_b32_e32 v42, 1.0
	v_mov_b32_e32 v34, 1.0
	v_mov_b32_e32 v40, 1.0
	v_mov_b32_e32 v36, 1.0
	s_cbranch_vccnz .LBB0_157
	s_waitcnt vmcnt(10)
	v_mov_b32_e32 v34, v184
	v_mov_b32_e32 v35, v185
	v_mov_b32_e32 v36, v186
	v_mov_b32_e32 v37, v187
	v_mov_b32_e32 v46, v188
	v_mov_b32_e32 v47, v189
	v_mov_b32_e32 v48, v190
	v_mov_b32_e32 v49, v191
	v_mov_b32_e32 v43, v34
	v_mov_b32_e32 v41, v36
	v_mov_b32_e32 v42, v46
	v_mov_b32_e32 v34, v47
	v_mov_b32_e32 v40, v48
	v_mov_b32_e32 v36, v49
.LBB0_157:
	v_mov_b64_e32 v[46:47], s[12:13]
	v_mad_i64_i32 v[44:45], s[0:1], v44, s43, v[46:47]
	v_pk_mul_f32 v[46:47], v[30:31], v[42:43]
	v_mov_b32_e32 v48, v37
	v_sub_f32_e32 v0, v46, v47
	v_mov_b32_e32 v46, v43
	v_mov_b32_e32 v47, v42
	v_pk_mul_f32 v[30:31], v[30:31], v[46:47]
	v_mov_b32_e32 v49, v36
	v_add_f32_e32 v50, v30, v31
	v_pk_mul_f32 v[30:31], v[32:33], v[34:35]
	v_lshl_add_u64 v[44:45], v[158:159], 1, v[44:45]
	v_sub_f32_e32 v51, v30, v31
	v_mov_b32_e32 v30, v35
	v_mov_b32_e32 v31, v34
	v_pk_mul_f32 v[32:33], v[32:33], v[30:31]
	s_nop 0
	v_add_f32_e32 v52, v32, v33
	v_pk_mul_f32 v[32:33], v[26:27], v[40:41]
	s_nop 0
	v_sub_f32_e32 v53, v32, v33
	v_mov_b32_e32 v32, v41
	v_mov_b32_e32 v33, v40
	v_pk_mul_f32 v[26:27], v[26:27], v[32:33]
	s_nop 0
	v_add_f32_e32 v54, v26, v27
	v_pk_mul_f32 v[26:27], v[28:29], v[36:37]
	s_nop 0
	v_sub_f32_e32 v55, v26, v27
	v_pk_mul_f32 v[26:27], v[28:29], v[48:49]
	s_nop 0
	v_add_f32_e32 v29, v26, v27
	v_cvt_pk_bf16_f32 v26, v0, v50
	v_cvt_pk_bf16_f32 v27, v51, v52
	v_cvt_pk_bf16_f32 v28, v53, v54
	v_cvt_pk_bf16_f32 v29, v55, v29
	global_store_dwordx4 v[44:45], v[26:29], off nt
	s_nop 1
	v_pk_mul_f32 v[26:27], v[22:23], v[42:43]
	v_pk_mul_f32 v[22:23], v[22:23], v[46:47]
	v_sub_f32_e32 v0, v26, v27
	v_add_f32_e32 v26, v22, v23
	v_pk_mul_f32 v[22:23], v[24:25], v[34:35]
	s_nop 0
	v_sub_f32_e32 v27, v22, v23
	v_pk_mul_f32 v[22:23], v[24:25], v[30:31]
	s_nop 0
	v_add_f32_e32 v24, v22, v23
	v_pk_mul_f32 v[22:23], v[18:19], v[40:41]
	v_pk_mul_f32 v[18:19], v[18:19], v[32:33]
	v_sub_f32_e32 v22, v22, v23
	v_add_f32_e32 v23, v18, v19
	v_pk_mul_f32 v[18:19], v[20:21], v[36:37]
	s_nop 0
	v_sub_f32_e32 v25, v18, v19
	v_pk_mul_f32 v[18:19], v[20:21], v[48:49]
	s_nop 0
	v_add_f32_e32 v21, v18, v19
	v_cvt_pk_bf16_f32 v18, v0, v26
	v_cvt_pk_bf16_f32 v19, v27, v24
	v_cvt_pk_bf16_f32 v20, v22, v23
	v_cvt_pk_bf16_f32 v21, v25, v21
	global_store_dwordx4 v[44:45], v[18:21], off offset:256 nt
	v_add_u32_e32 v24, 0xb0, v170
	s_and_b64 vcc, exec, s[8:9]
	v_mov_b32_e32 v19, 0
	v_mov_b32_e32 v23, 0
	v_mov_b32_e32 v21, 0
	v_mov_b32_e32 v18, 1.0
	v_mov_b32_e32 v22, 1.0
	v_mov_b32_e32 v20, 1.0
	s_cbranch_vccnz .LBB0_159
	s_waitcnt vmcnt(10)
	v_mov_b32_e32 v18, v192
	v_mov_b32_e32 v19, v193
	v_mov_b32_e32 v20, v194
	v_mov_b32_e32 v21, v195
	v_mov_b32_e32 v26, v196
	v_mov_b32_e32 v27, v197
	v_mov_b32_e32 v28, v198
	v_mov_b32_e32 v29, v199
	v_mov_b32_e32 v39, v18
	v_mov_b32_e32 v23, v20
	v_mov_b32_e32 v38, v26
	v_mov_b32_e32 v18, v27
	v_mov_b32_e32 v22, v28
	v_mov_b32_e32 v20, v29
.LBB0_159:
	v_mov_b64_e32 v[26:27], s[12:13]
	v_mad_i64_i32 v[24:25], s[0:1], v24, s43, v[26:27]
	v_pk_mul_f32 v[26:27], v[14:15], v[38:39]
	v_mov_b32_e32 v28, v21
	v_sub_f32_e32 v0, v26, v27
	v_mov_b32_e32 v26, v39
	v_mov_b32_e32 v27, v38
	v_pk_mul_f32 v[14:15], v[14:15], v[26:27]
	v_mov_b32_e32 v29, v20
	v_add_f32_e32 v30, v14, v15
	v_pk_mul_f32 v[14:15], v[16:17], v[18:19]
	v_lshl_add_u64 v[24:25], v[158:159], 1, v[24:25]
	v_sub_f32_e32 v31, v14, v15
	v_mov_b32_e32 v14, v19
	v_mov_b32_e32 v15, v18
	v_pk_mul_f32 v[16:17], v[16:17], v[14:15]
	s_nop 0
	v_add_f32_e32 v32, v16, v17
	v_pk_mul_f32 v[16:17], v[10:11], v[22:23]
	s_nop 0
	v_sub_f32_e32 v33, v16, v17
	v_mov_b32_e32 v16, v23
	v_mov_b32_e32 v17, v22
	v_pk_mul_f32 v[10:11], v[10:11], v[16:17]
	s_nop 0
	v_add_f32_e32 v34, v10, v11
	v_pk_mul_f32 v[10:11], v[12:13], v[20:21]
	s_nop 0
	v_sub_f32_e32 v35, v10, v11
	v_pk_mul_f32 v[10:11], v[12:13], v[28:29]
	s_nop 0
	v_add_f32_e32 v13, v10, v11
	v_cvt_pk_bf16_f32 v10, v0, v30
	v_cvt_pk_bf16_f32 v11, v31, v32
	v_cvt_pk_bf16_f32 v12, v33, v34
	v_cvt_pk_bf16_f32 v13, v35, v13
	global_store_dwordx4 v[24:25], v[10:13], off nt
	s_nop 1
	v_pk_mul_f32 v[10:11], v[6:7], v[38:39]
	v_pk_mul_f32 v[6:7], v[6:7], v[26:27]
	v_sub_f32_e32 v0, v10, v11
	v_add_f32_e32 v10, v6, v7
	v_pk_mul_f32 v[6:7], v[8:9], v[18:19]
	s_nop 0
	v_sub_f32_e32 v11, v6, v7
	v_pk_mul_f32 v[6:7], v[8:9], v[14:15]
	s_nop 0
	v_add_f32_e32 v8, v6, v7
	v_pk_mul_f32 v[6:7], v[2:3], v[22:23]
	v_pk_mul_f32 v[2:3], v[2:3], v[16:17]
	v_sub_f32_e32 v6, v6, v7
	v_add_f32_e32 v7, v2, v3
	v_pk_mul_f32 v[2:3], v[4:5], v[20:21]
	s_nop 0
	v_sub_f32_e32 v9, v2, v3
	v_pk_mul_f32 v[2:3], v[4:5], v[28:29]
	s_nop 0
	v_add_f32_e32 v5, v2, v3
	v_cvt_pk_bf16_f32 v2, v0, v10
	v_cvt_pk_bf16_f32 v3, v11, v8
	v_cvt_pk_bf16_f32 v4, v6, v7
	v_cvt_pk_bf16_f32 v5, v9, v5
	global_store_dwordx4 v[24:25], v[2:5], off offset:256 nt

.Lepi_fast:
	v_lshl_or_b32 v158, s55, 8, v168
	v_ashrrev_i32_e32 v159, 31, v158
	v_mov_b64_e32 v[172:173], s[12:13]
	v_mad_i64_i32 v[172:173], s[0:1], v170, s43, v[172:173]
	v_cvt_pk_bf16_f32 v126, v126, v127
	v_cvt_pk_bf16_f32 v127, v128, v129
	v_cvt_pk_bf16_f32 v128, v122, v123
	v_cvt_pk_bf16_f32 v129, v124, v125
	v_lshl_add_u64 v[172:173], v[158:159], 1, v[172:173]
	v_cvt_pk_bf16_f32 v118, v118, v119
	v_cvt_pk_bf16_f32 v119, v120, v121
	v_cvt_pk_bf16_f32 v120, v114, v115
	v_cvt_pk_bf16_f32 v121, v116, v117
	global_store_dwordx4 v[172:173], v[126:129], off nt
	global_store_dwordx4 v[172:173], v[118:121], off offset:256 nt
	v_add_u32_e32 v174, 16, v170
	v_mov_b64_e32 v[172:173], s[12:13]
	v_mad_i64_i32 v[172:173], s[0:1], v174, s43, v[172:173]
	v_cvt_pk_bf16_f32 v110, v110, v111
	v_cvt_pk_bf16_f32 v111, v112, v113
	v_cvt_pk_bf16_f32 v112, v106, v107
	v_cvt_pk_bf16_f32 v113, v108, v109
	v_lshl_add_u64 v[172:173], v[158:159], 1, v[172:173]
	v_cvt_pk_bf16_f32 v102, v102, v103
	v_cvt_pk_bf16_f32 v103, v104, v105
	v_cvt_pk_bf16_f32 v104, v98, v99
	v_cvt_pk_bf16_f32 v105, v100, v101
	global_store_dwordx4 v[172:173], v[110:113], off nt
	global_store_dwordx4 v[172:173], v[102:105], off offset:256 nt
	v_add_u32_e32 v174, 32, v170
	v_mov_b64_e32 v[172:173], s[12:13]
	v_mad_i64_i32 v[172:173], s[0:1], v174, s43, v[172:173]
	v_cvt_pk_bf16_f32 v94, v94, v95
	v_cvt_pk_bf16_f32 v95, v96, v97
	v_cvt_pk_bf16_f32 v96, v90, v91
	v_cvt_pk_bf16_f32 v97, v92, v93
	v_lshl_add_u64 v[172:173], v[158:159], 1, v[172:173]
	v_cvt_pk_bf16_f32 v86, v86, v87
	v_cvt_pk_bf16_f32 v87, v88, v89
	v_cvt_pk_bf16_f32 v88, v82, v83
	v_cvt_pk_bf16_f32 v89, v84, v85
	global_store_dwordx4 v[172:173], v[94:97], off nt
	global_store_dwordx4 v[172:173], v[86:89], off offset:256 nt
	v_add_u32_e32 v174, 48, v170
	v_mov_b64_e32 v[172:173], s[12:13]
	v_mad_i64_i32 v[172:173], s[0:1], v174, s43, v[172:173]
	v_cvt_pk_bf16_f32 v78, v78, v79
	v_cvt_pk_bf16_f32 v79, v80, v81
	v_cvt_pk_bf16_f32 v80, v74, v75
	v_cvt_pk_bf16_f32 v81, v76, v77
	v_lshl_add_u64 v[172:173], v[158:159], 1, v[172:173]
	v_cvt_pk_bf16_f32 v70, v70, v71
	v_cvt_pk_bf16_f32 v71, v72, v73
	v_cvt_pk_bf16_f32 v72, v66, v67
	v_cvt_pk_bf16_f32 v73, v68, v69
	global_store_dwordx4 v[172:173], v[78:81], off nt
	global_store_dwordx4 v[172:173], v[70:73], off offset:256 nt
	v_add_u32_e32 v174, 0x80, v170
	v_mov_b64_e32 v[172:173], s[12:13]
	v_mad_i64_i32 v[172:173], s[0:1], v174, s43, v[172:173]
	v_cvt_pk_bf16_f32 v62, v62, v63
	v_cvt_pk_bf16_f32 v63, v64, v65
	v_cvt_pk_bf16_f32 v64, v58, v59
	v_cvt_pk_bf16_f32 v65, v60, v61
	v_lshl_add_u64 v[172:173], v[158:159], 1, v[172:173]
	v_cvt_pk_bf16_f32 v54, v54, v55
	v_cvt_pk_bf16_f32 v55, v56, v57
	v_cvt_pk_bf16_f32 v56, v50, v51
	v_cvt_pk_bf16_f32 v57, v52, v53
	global_store_dwordx4 v[172:173], v[62:65], off nt
	global_store_dwordx4 v[172:173], v[54:57], off offset:256 nt
	v_add_u32_e32 v174, 0x90, v170
	v_mov_b64_e32 v[172:173], s[12:13]
	v_mad_i64_i32 v[172:173], s[0:1], v174, s43, v[172:173]
	v_cvt_pk_bf16_f32 v46, v46, v47
	v_cvt_pk_bf16_f32 v47, v48, v49
	v_cvt_pk_bf16_f32 v48, v42, v43
	v_cvt_pk_bf16_f32 v49, v44, v45
	v_lshl_add_u64 v[172:173], v[158:159], 1, v[172:173]
	v_cvt_pk_bf16_f32 v38, v38, v39
	v_cvt_pk_bf16_f32 v39, v40, v41
	v_cvt_pk_bf16_f32 v40, v34, v35
	v_cvt_pk_bf16_f32 v41, v36, v37
	global_store_dwordx4 v[172:173], v[46:49], off nt
	global_store_dwordx4 v[172:173], v[38:41], off offset:256 nt
	v_add_u32_e32 v174, 0xa0, v170
	v_mov_b64_e32 v[172:173], s[12:13]
	v_mad_i64_i32 v[172:173], s[0:1], v174, s43, v[172:173]
	v_cvt_pk_bf16_f32 v30, v30, v31
	v_cvt_pk_bf16_f32 v31, v32, v33
	v_cvt_pk_bf16_f32 v32, v26, v27
	v_cvt_pk_bf16_f32 v33, v28, v29
	v_lshl_add_u64 v[172:173], v[158:159], 1, v[172:173]
	v_cvt_pk_bf16_f32 v22, v22, v23
	v_cvt_pk_bf16_f32 v23, v24, v25
	v_cvt_pk_bf16_f32 v24, v18, v19
	v_cvt_pk_bf16_f32 v25, v20, v21
	global_store_dwordx4 v[172:173], v[30:33], off nt
	global_store_dwordx4 v[172:173], v[22:25], off offset:256 nt
	v_add_u32_e32 v174, 0xb0, v170
	v_mov_b64_e32 v[172:173], s[12:13]
	v_mad_i64_i32 v[172:173], s[0:1], v174, s43, v[172:173]
	v_cvt_pk_bf16_f32 v14, v14, v15
	v_cvt_pk_bf16_f32 v15, v16, v17
	v_cvt_pk_bf16_f32 v16, v10, v11
	v_cvt_pk_bf16_f32 v17, v12, v13
	v_lshl_add_u64 v[172:173], v[158:159], 1, v[172:173]
	v_cvt_pk_bf16_f32 v6, v6, v7
	v_cvt_pk_bf16_f32 v7, v8, v9
	v_cvt_pk_bf16_f32 v8, v2, v3
	v_cvt_pk_bf16_f32 v9, v4, v5
	global_store_dwordx4 v[172:173], v[14:17], off nt
	global_store_dwordx4 v[172:173], v[6:9], off offset:256 nt
	s_branch .Lepi_join

.LBB0_405:
	v_max3_f32 v0, v66, v67, v68
	v_max3_f32 v95, v69, v70, v71
	v_max3_f32 v204, v72, v73, v74
	v_max3_f32 v0, v0, v75, v76
	v_max3_f32 v95, v95, v77, v78
	v_max3_f32 v204, v204, v79, v80
	v_max3_f32 v0, v0, v95, v204
	v_max_f32_e32 v0, v0, v81
	v_mov_b32_e32 v95, v0
	s_nop 1
	v_permlane32_swap_b32_e32 v95, v0
	s_nop 0
	v_max3_f32 v95, v199, v0, v95
	v_sub_f32_e32 v0, v199, v95
	v_exp_f32_e32 v0, v0
	v_sub_f32_e32 v66, v66, v95
	v_sub_f32_e32 v67, v67, v95
	v_exp_f32_e32 v66, v66
	v_sub_f32_e32 v68, v68, v95
	v_exp_f32_e32 v67, v67
	v_sub_f32_e32 v69, v69, v95
	v_exp_f32_e32 v68, v68
	v_sub_f32_e32 v70, v70, v95
	v_add_f32_e32 v204, v67, v66
	v_exp_f32_e32 v69, v69
	v_sub_f32_e32 v71, v71, v95
	v_add_f32_e32 v204, v68, v204
	v_exp_f32_e32 v70, v70
	v_sub_f32_e32 v72, v72, v95
	v_add_f32_e32 v204, v69, v204
	v_exp_f32_e32 v71, v71
	v_sub_f32_e32 v73, v73, v95
	v_add_f32_e32 v204, v70, v204
	v_exp_f32_e32 v72, v72
	v_sub_f32_e32 v74, v74, v95
	v_add_f32_e32 v204, v71, v204
	v_exp_f32_e32 v73, v73
	v_sub_f32_e32 v75, v75, v95
	v_add_f32_e32 v204, v72, v204
	v_exp_f32_e32 v74, v74
	v_sub_f32_e32 v76, v76, v95
	v_add_f32_e32 v204, v73, v204
	v_exp_f32_e32 v75, v75
	v_sub_f32_e32 v77, v77, v95
	v_add_f32_e32 v204, v74, v204
	v_exp_f32_e32 v76, v76
	v_sub_f32_e32 v78, v78, v95
	v_add_f32_e32 v204, v75, v204
	v_exp_f32_e32 v77, v77
	v_sub_f32_e32 v79, v79, v95
	v_add_f32_e32 v204, v76, v204
	v_exp_f32_e32 v78, v78
	v_sub_f32_e32 v80, v80, v95
	v_add_f32_e32 v204, v77, v204
	v_exp_f32_e32 v79, v79
	v_sub_f32_e32 v81, v81, v95
	v_add_f32_e32 v204, v78, v204
	v_exp_f32_e32 v80, v80
	v_add_f32_e32 v204, v79, v204
	v_exp_f32_e32 v81, v81
	v_add_f32_e32 v204, v80, v204
	v_add_f32_e32 v204, v81, v204
	v_fmac_f32_e32 v204, v198, v0
	v_cvt_pk_bf16_f32 v244, v66, v67
	v_cvt_pk_bf16_f32 v245, v68, v69
	v_cvt_pk_bf16_f32 v246, v70, v71
	v_cvt_pk_bf16_f32 v247, v72, v73
	v_cvt_pk_bf16_f32 v66, v74, v75
	v_cvt_pk_bf16_f32 v67, v76, v77
	v_cvt_pk_bf16_f32 v68, v78, v79
	v_cvt_pk_bf16_f32 v69, v80, v81
	s_waitcnt lgkmcnt(8)
	v_pk_mul_f32 v[50:51], v[50:51], v[0:1] op_sel_hi:[1,0]
	v_pk_mul_f32 v[52:53], v[52:53], v[0:1] op_sel_hi:[1,0]
	v_pk_mul_f32 v[54:55], v[54:55], v[0:1] op_sel_hi:[1,0]
	v_pk_mul_f32 v[56:57], v[56:57], v[0:1] op_sel_hi:[1,0]
	v_pk_mul_f32 v[58:59], v[58:59], v[0:1] op_sel_hi:[1,0]
	v_pk_mul_f32 v[60:61], v[60:61], v[0:1] op_sel_hi:[1,0]
	v_pk_mul_f32 v[62:63], v[62:63], v[0:1] op_sel_hi:[1,0]
	v_pk_mul_f32 v[64:65], v[64:65], v[0:1] op_sel_hi:[1,0]
	v_pk_mul_f32 v[34:35], v[34:35], v[0:1] op_sel_hi:[1,0]
	v_pk_mul_f32 v[36:37], v[36:37], v[0:1] op_sel_hi:[1,0]
	v_mfma_f32_32x32x16_bf16 v[50:65], v[216:219], v[244:247], v[50:65]
	v_pk_mul_f32 v[38:39], v[38:39], v[0:1] op_sel_hi:[1,0]
	v_pk_mul_f32 v[40:41], v[40:41], v[0:1] op_sel_hi:[1,0]
	v_pk_mul_f32 v[42:43], v[42:43], v[0:1] op_sel_hi:[1,0]
	v_pk_mul_f32 v[44:45], v[44:45], v[0:1] op_sel_hi:[1,0]
	v_pk_mul_f32 v[46:47], v[46:47], v[0:1] op_sel_hi:[1,0]
	v_pk_mul_f32 v[48:49], v[48:49], v[0:1] op_sel_hi:[1,0]
	v_pk_mul_f32 v[18:19], v[18:19], v[0:1] op_sel_hi:[1,0]
	v_pk_mul_f32 v[20:21], v[20:21], v[0:1] op_sel_hi:[1,0]
	v_mfma_f32_32x32x16_bf16 v[34:49], v[220:223], v[244:247], v[34:49]
	v_pk_mul_f32 v[22:23], v[22:23], v[0:1] op_sel_hi:[1,0]
	v_pk_mul_f32 v[24:25], v[24:25], v[0:1] op_sel_hi:[1,0]
	v_pk_mul_f32 v[26:27], v[26:27], v[0:1] op_sel_hi:[1,0]
	v_pk_mul_f32 v[28:29], v[28:29], v[0:1] op_sel_hi:[1,0]
	v_pk_mul_f32 v[30:31], v[30:31], v[0:1] op_sel_hi:[1,0]
	v_pk_mul_f32 v[32:33], v[32:33], v[0:1] op_sel_hi:[1,0]
	v_pk_mul_f32 v[2:3], v[2:3], v[0:1] op_sel_hi:[1,0]
	v_pk_mul_f32 v[4:5], v[4:5], v[0:1] op_sel_hi:[1,0]
	v_mfma_f32_32x32x16_bf16 v[18:33], v[224:227], v[244:247], v[18:33]
	v_pk_mul_f32 v[6:7], v[6:7], v[0:1] op_sel_hi:[1,0]
	v_pk_mul_f32 v[8:9], v[8:9], v[0:1] op_sel_hi:[1,0]
	v_pk_mul_f32 v[10:11], v[10:11], v[0:1] op_sel_hi:[1,0]
	v_pk_mul_f32 v[12:13], v[12:13], v[0:1] op_sel_hi:[1,0]
	v_pk_mul_f32 v[14:15], v[14:15], v[0:1] op_sel_hi:[1,0]
	v_pk_mul_f32 v[16:17], v[16:17], v[0:1] op_sel_hi:[1,0]
	v_mov_b32_e32 v198, v204
	v_mov_b32_e32 v199, v95
	v_mfma_f32_32x32x16_bf16 v[2:17], v[200:203], v[244:247], v[2:17]
	s_waitcnt lgkmcnt(0)
	v_mfma_f32_32x32x16_bf16 v[50:65], v[228:231], v[66:69], v[50:65]
	v_mfma_f32_32x32x16_bf16 v[34:49], v[232:235], v[66:69], v[34:49]
	v_mfma_f32_32x32x16_bf16 v[18:33], v[236:239], v[66:69], v[18:33]
	v_mfma_f32_32x32x16_bf16 v[2:17], v[240:243], v[66:69], v[2:17]

.LBB0_475:
	s_lshl_b32 s0, s59, 14
	s_xor_b64 s[10:11], s[10:11], -1
	v_add_u32_e32 v201, s0, v204
	v_add_u32_e32 v202, s0, v215
	v_xor_b32_e32 v0, 32, v201
	v_xor_b32_e32 v95, 64, v201
	ds_read_b128 v[66:69], v201
	ds_read_b128 v[216:219], v0
	v_xor_b32_e32 v0, 0x60, v201
	ds_read_b128 v[220:223], v95
	v_xor_b32_e32 v95, 0x80, v201
	ds_read_b128 v[224:227], v0
	v_xor_b32_e32 v0, 0xa0, v201
	ds_read_b128 v[228:231], v95
	v_xor_b32_e32 v95, 0xc0, v201
	ds_read_b128 v[232:235], v0
	v_xor_b32_e32 v0, 0xe0, v201
	ds_read_b128 v[236:239], v95
	ds_read_b128 v[240:243], v0
	s_waitcnt lgkmcnt(7)
	v_mfma_f32_32x32x16_bf16 v[66:81], v[66:69], v[82:85], 0
	v_and_b32_e32 v251, 64, v207
	v_xor_b32_e32 v250, 32, v207
	v_add_u32_e32 v251, 64, v251
	v_cmp_lt_i32_e32 vcc, v250, v251
	s_nop 1
	v_cndmask_b32_e32 v250, v207, v250, vcc
	v_lshlrev_b32_e32 v200, 2, v250
	s_waitcnt lgkmcnt(6)
	v_mfma_f32_32x32x16_bf16 v[66:81], v[216:219], v[86:89], v[66:81]
	s_waitcnt lgkmcnt(5)
	v_mfma_f32_32x32x16_bf16 v[66:81], v[220:223], v[90:93], v[66:81]
	s_waitcnt lgkmcnt(4)
	v_mfma_f32_32x32x16_bf16 v[66:81], v[224:227], v[128:131], v[66:81]
	s_waitcnt lgkmcnt(3)
	v_mfma_f32_32x32x16_bf16 v[66:81], v[228:231], v[132:135], v[66:81]
	s_waitcnt lgkmcnt(2)
	v_mfma_f32_32x32x16_bf16 v[66:81], v[232:235], v[136:139], v[66:81]
	s_waitcnt lgkmcnt(1)
	v_mfma_f32_32x32x16_bf16 v[66:81], v[236:239], v[140:143], v[66:81]
	s_waitcnt lgkmcnt(0)
	v_mfma_f32_32x32x16_bf16 v[66:81], v[240:243], v[144:147], v[66:81]
	v_xor_b32_e32 v0, 0x820, v202
	v_xor_b32_e32 v95, 64, v202
	v_xor_b32_e32 v203, 0x860, v202
	v_xor_b32_e32 v244, 0x80, v202
	v_xor_b32_e32 v245, 0x8a0, v202
	v_xor_b32_e32 v246, 0xc0, v202
	v_xor_b32_e32 v247, 0x8e0, v202
	ds_read_b64_tr_b16 v[216:217], v202
	ds_read_b64_tr_b16 v[218:219], v0
	ds_read_b64_tr_b16 v[220:221], v95
	ds_read_b64_tr_b16 v[222:223], v203
	ds_read_b64_tr_b16 v[224:225], v244
	ds_read_b64_tr_b16 v[226:227], v245
	ds_read_b64_tr_b16 v[248:249], v246
	ds_read_b64_tr_b16 v[250:251], v247
	ds_read_b64_tr_b16 v[228:229], v202 offset:4096
	ds_read_b64_tr_b16 v[230:231], v0 offset:4096
	ds_read_b64_tr_b16 v[232:233], v95 offset:4096
	ds_read_b64_tr_b16 v[234:235], v203 offset:4096
	ds_read_b64_tr_b16 v[236:237], v244 offset:4096
	ds_read_b64_tr_b16 v[238:239], v245 offset:4096
	ds_read_b64_tr_b16 v[240:241], v246 offset:4096
	ds_read_b64_tr_b16 v[242:243], v247 offset:4096
	v_max3_f32 v0, v66, v67, v68
	v_max3_f32 v95, v69, v70, v71
	v_max3_f32 v201, v72, v73, v74
	v_max3_f32 v0, v0, v75, v76
	v_max3_f32 v95, v95, v77, v78
	v_max3_f32 v201, v201, v79, v80
	v_max3_f32 v0, v0, v95, v201
	v_max_f32_e32 v0, v0, v81
	v_mov_b32_e32 v95, v0
	s_nop 1
	v_permlane32_swap_b32_e32 v95, v0
	s_nop 0
	v_max3_f32 v95, v199, v0, v95
	v_sub_f32_e32 v0, v199, v95
	v_exp_f32_e32 v0, v0
	v_sub_f32_e32 v66, v66, v95
	v_sub_f32_e32 v67, v67, v95
	v_exp_f32_e32 v66, v66
	v_sub_f32_e32 v68, v68, v95
	v_exp_f32_e32 v67, v67
	v_sub_f32_e32 v69, v69, v95
	v_exp_f32_e32 v68, v68
	v_sub_f32_e32 v70, v70, v95
	v_add_f32_e32 v201, v67, v66
	v_exp_f32_e32 v69, v69
	v_sub_f32_e32 v71, v71, v95
	v_add_f32_e32 v201, v68, v201
	v_exp_f32_e32 v70, v70
	v_sub_f32_e32 v72, v72, v95
	v_add_f32_e32 v201, v69, v201
	v_exp_f32_e32 v71, v71
	v_sub_f32_e32 v73, v73, v95
	v_add_f32_e32 v201, v70, v201
	v_exp_f32_e32 v72, v72
	v_sub_f32_e32 v74, v74, v95
	v_add_f32_e32 v201, v71, v201
	v_exp_f32_e32 v73, v73
	v_sub_f32_e32 v75, v75, v95
	v_add_f32_e32 v201, v72, v201
	v_exp_f32_e32 v74, v74
	v_sub_f32_e32 v76, v76, v95
	v_add_f32_e32 v201, v73, v201
	v_exp_f32_e32 v75, v75
	v_sub_f32_e32 v77, v77, v95
	v_add_f32_e32 v201, v74, v201
	v_exp_f32_e32 v76, v76
	v_sub_f32_e32 v78, v78, v95
	v_add_f32_e32 v201, v75, v201
	v_exp_f32_e32 v77, v77
	v_sub_f32_e32 v79, v79, v95
	v_add_f32_e32 v201, v76, v201
	v_exp_f32_e32 v78, v78
	v_sub_f32_e32 v80, v80, v95
	v_add_f32_e32 v201, v77, v201
	v_exp_f32_e32 v79, v79
	v_sub_f32_e32 v81, v81, v95
	v_add_f32_e32 v201, v78, v201
	v_exp_f32_e32 v80, v80
	v_add_f32_e32 v201, v79, v201
	v_exp_f32_e32 v81, v81
	v_add_f32_e32 v201, v80, v201
	v_add_f32_e32 v201, v81, v201
	v_fmac_f32_e32 v201, v198, v0
	v_cvt_pk_bf16_f32 v244, v66, v67
	v_cvt_pk_bf16_f32 v245, v68, v69
	v_cvt_pk_bf16_f32 v246, v70, v71
	v_cvt_pk_bf16_f32 v247, v72, v73
	v_cvt_pk_bf16_f32 v66, v74, v75
	v_cvt_pk_bf16_f32 v67, v76, v77
	v_cvt_pk_bf16_f32 v68, v78, v79
	v_cvt_pk_bf16_f32 v69, v80, v81
	s_waitcnt lgkmcnt(8)
	v_pk_mul_f32 v[50:51], v[50:51], v[0:1] op_sel_hi:[1,0]
	v_pk_mul_f32 v[52:53], v[52:53], v[0:1] op_sel_hi:[1,0]
	v_pk_mul_f32 v[54:55], v[54:55], v[0:1] op_sel_hi:[1,0]
	v_pk_mul_f32 v[56:57], v[56:57], v[0:1] op_sel_hi:[1,0]
	v_pk_mul_f32 v[58:59], v[58:59], v[0:1] op_sel_hi:[1,0]
	v_pk_mul_f32 v[60:61], v[60:61], v[0:1] op_sel_hi:[1,0]
	v_pk_mul_f32 v[62:63], v[62:63], v[0:1] op_sel_hi:[1,0]
	v_pk_mul_f32 v[64:65], v[64:65], v[0:1] op_sel_hi:[1,0]
	v_pk_mul_f32 v[34:35], v[34:35], v[0:1] op_sel_hi:[1,0]
	v_pk_mul_f32 v[36:37], v[36:37], v[0:1] op_sel_hi:[1,0]
	v_mfma_f32_32x32x16_bf16 v[50:65], v[216:219], v[244:247], v[50:65]
	v_pk_mul_f32 v[38:39], v[38:39], v[0:1] op_sel_hi:[1,0]
	v_pk_mul_f32 v[40:41], v[40:41], v[0:1] op_sel_hi:[1,0]
	v_pk_mul_f32 v[42:43], v[42:43], v[0:1] op_sel_hi:[1,0]
	v_pk_mul_f32 v[44:45], v[44:45], v[0:1] op_sel_hi:[1,0]
	v_pk_mul_f32 v[46:47], v[46:47], v[0:1] op_sel_hi:[1,0]
	v_pk_mul_f32 v[48:49], v[48:49], v[0:1] op_sel_hi:[1,0]
	v_pk_mul_f32 v[18:19], v[18:19], v[0:1] op_sel_hi:[1,0]
	v_pk_mul_f32 v[20:21], v[20:21], v[0:1] op_sel_hi:[1,0]
	v_mfma_f32_32x32x16_bf16 v[34:49], v[220:223], v[244:247], v[34:49]
	v_pk_mul_f32 v[22:23], v[22:23], v[0:1] op_sel_hi:[1,0]
	v_pk_mul_f32 v[24:25], v[24:25], v[0:1] op_sel_hi:[1,0]
	v_pk_mul_f32 v[26:27], v[26:27], v[0:1] op_sel_hi:[1,0]
	v_pk_mul_f32 v[28:29], v[28:29], v[0:1] op_sel_hi:[1,0]
	v_pk_mul_f32 v[30:31], v[30:31], v[0:1] op_sel_hi:[1,0]
	v_pk_mul_f32 v[32:33], v[32:33], v[0:1] op_sel_hi:[1,0]
	v_pk_mul_f32 v[2:3], v[2:3], v[0:1] op_sel_hi:[1,0]
	v_pk_mul_f32 v[4:5], v[4:5], v[0:1] op_sel_hi:[1,0]
	v_mfma_f32_32x32x16_bf16 v[18:33], v[224:227], v[244:247], v[18:33]
	v_pk_mul_f32 v[6:7], v[6:7], v[0:1] op_sel_hi:[1,0]
	v_pk_mul_f32 v[8:9], v[8:9], v[0:1] op_sel_hi:[1,0]
	v_pk_mul_f32 v[10:11], v[10:11], v[0:1] op_sel_hi:[1,0]
	v_pk_mul_f32 v[12:13], v[12:13], v[0:1] op_sel_hi:[1,0]
	v_pk_mul_f32 v[14:15], v[14:15], v[0:1] op_sel_hi:[1,0]
	v_pk_mul_f32 v[16:17], v[16:17], v[0:1] op_sel_hi:[1,0]
	v_mov_b32_e32 v198, v201
	v_mov_b32_e32 v199, v95
	v_mfma_f32_32x32x16_bf16 v[2:17], v[248:251], v[244:247], v[2:17]
	s_waitcnt lgkmcnt(0)
	v_mfma_f32_32x32x16_bf16 v[50:65], v[228:231], v[66:69], v[50:65]
	v_mfma_f32_32x32x16_bf16 v[34:49], v[232:235], v[66:69], v[34:49]
	v_mfma_f32_32x32x16_bf16 v[18:33], v[236:239], v[66:69], v[18:33]
	v_mfma_f32_32x32x16_bf16 v[2:17], v[240:243], v[66:69], v[2:17]
	v_mov_b32_e32 v68, v201
	s_mov_b64 s[0:1], -1
	s_andn2_b64 vcc, exec, s[10:11]
	s_cbranch_vccnz .LBB0_479
	s_waitcnt vmcnt(4)
	s_mov_b64 s[0:1], 0

.LBB0_496:
	s_waitcnt lgkmcnt(0)
	v_add_f32_e32 v0, v68, v69
	v_rcp_f32_e32 v66, v0
	s_ashr_i32 s0, s58, 5
	s_lshl_b32 s10, s58, 8
	s_ashr_i32 s1, s0, 31
	s_and_b32 s10, s10, 0x700
	s_lshl_b64 s[0:1], s[0:1], 11
	s_add_i32 s10, s10, s31
	v_pk_mul_f32 v[34:35], v[34:35], v[66:67] op_sel_hi:[1,0]
	v_pk_mul_f32 v[36:37], v[36:37], v[66:67] op_sel_hi:[1,0]
	s_add_u32 s16, s0, s10
	v_cvt_pk_bf16_f32 v34, v34, v35
	v_cvt_pk_bf16_f32 v35, v36, v37
	v_pk_mul_f32 v[36:37], v[38:39], v[66:67] op_sel_hi:[1,0]
	v_pk_mul_f32 v[38:39], v[40:41], v[66:67] op_sel_hi:[1,0]
	s_addc_u32 s0, s1, 0
	v_cvt_pk_bf16_f32 v36, v36, v37
	v_cvt_pk_bf16_f32 v37, v38, v39
	s_lshl_b32 s1, s58, 5
	v_pk_mul_f32 v[50:51], v[50:51], v[66:67] op_sel_hi:[1,0]
	v_pk_mul_f32 v[52:53], v[52:53], v[66:67] op_sel_hi:[1,0]
	ds_write2_b64 v197, v[34:35], v[36:37] offset0:8 offset1:10
	v_pk_mul_f32 v[34:35], v[42:43], v[66:67] op_sel_hi:[1,0]
	v_pk_mul_f32 v[36:37], v[44:45], v[66:67] op_sel_hi:[1,0]
	s_and_b32 s10, s1, 0x300
	v_cvt_pk_bf16_f32 v50, v50, v51
	v_cvt_pk_bf16_f32 v51, v52, v53
	v_pk_mul_f32 v[52:53], v[54:55], v[66:67] op_sel_hi:[1,0]
	v_pk_mul_f32 v[54:55], v[56:57], v[66:67] op_sel_hi:[1,0]
	v_cvt_pk_bf16_f32 v34, v34, v35
	v_cvt_pk_bf16_f32 v35, v36, v37
	v_pk_mul_f32 v[36:37], v[46:47], v[66:67] op_sel_hi:[1,0]
	v_pk_mul_f32 v[38:39], v[48:49], v[66:67] op_sel_hi:[1,0]
	s_add_u32 s14, s96, s10
	v_cvt_pk_bf16_f32 v52, v52, v53
	v_cvt_pk_bf16_f32 v53, v54, v55
	v_cvt_pk_bf16_f32 v36, v36, v37
	v_cvt_pk_bf16_f32 v37, v38, v39
	s_addc_u32 s15, s97, 0
	ds_write2_b64 v197, v[50:51], v[52:53] offset1:2
	v_pk_mul_f32 v[50:51], v[58:59], v[66:67] op_sel_hi:[1,0]
	v_pk_mul_f32 v[52:53], v[60:61], v[66:67] op_sel_hi:[1,0]
	v_pk_mul_f32 v[54:55], v[64:65], v[66:67] op_sel_hi:[1,0]
	ds_write2_b64 v197, v[34:35], v[36:37] offset0:12 offset1:14
	v_or_b32_e32 v64, s16, v164
	v_mov_b64_e32 v[34:35], s[14:15]
	v_cvt_pk_bf16_f32 v50, v50, v51
	v_cvt_pk_bf16_f32 v51, v52, v53
	v_pk_mul_f32 v[52:53], v[62:63], v[66:67] op_sel_hi:[1,0]
	v_mad_u64_u32 v[36:37], s[14:15], v64, s43, v[34:35]
	v_cvt_pk_bf16_f32 v52, v52, v53
	v_cvt_pk_bf16_f32 v53, v54, v55
	v_mad_i32_i24 v37, s0, v211, v37
	s_mov_b64 s[24:25], 0x3400
	ds_write2_b64 v197, v[50:51], v[52:53] offset0:4 offset1:6
	v_lshl_add_u64 v[42:43], v[36:37], 0, s[24:25]
	v_lshlrev_b32_e32 v0, 1, v166
	s_waitcnt lgkmcnt(0)
	v_lshl_add_u64 v[36:37], v[42:43], 0, v[0:1]
	flat_load_dwordx4 v[50:53], v[36:37]
	v_or_b32_e32 v72, s16, v168
	v_mad_u64_u32 v[36:37], s[14:15], v72, s43, v[34:35]
	v_mad_i32_i24 v37, s0, v211, v37
	v_lshl_add_u64 v[48:49], v[36:37], 0, s[24:25]
	v_lshl_add_u64 v[36:37], v[48:49], 0, v[0:1]
	flat_load_dwordx4 v[68:71], v[36:37]
	v_or_b32_e32 v56, s16, v170
	v_or_b32_e32 v54, s16, v172
	v_mad_u64_u32 v[38:39], s[14:15], v56, s43, v[34:35]
	v_mad_u64_u32 v[34:35], s[14:15], v54, s43, v[34:35]
	v_mad_i32_i24 v39, s0, v211, v39
	v_mad_i32_i24 v35, s0, v211, v35
	v_lshl_add_u64 v[44:45], v[38:39], 0, s[24:25]
	v_lshl_add_u64 v[46:47], v[34:35], 0, s[24:25]
	v_add_u32_e32 v58, v185, v186
	v_lshl_add_u64 v[34:35], v[44:45], 0, v[0:1]
	v_lshl_add_u64 v[36:37], v[46:47], 0, v[0:1]
	ds_read_b128 v[60:63], v58
	flat_load_dwordx4 v[38:41], v[34:35]
	s_nop 0
	flat_load_dwordx4 v[34:37], v[36:37]
	v_lshlrev_b32_e32 v232, 1, v174
	v_mov_b32_e32 v233, 0
	v_lshl_add_u64 v[234:235], v[42:43], 0, v[232:233]
	global_load_dwordx4 v[216:219], v[234:235], off
	v_lshl_add_u64 v[234:235], v[48:49], 0, v[232:233]
	global_load_dwordx4 v[220:223], v[234:235], off
	v_lshl_add_u64 v[234:235], v[44:45], 0, v[232:233]
	global_load_dwordx4 v[224:227], v[234:235], off
	v_lshl_add_u64 v[234:235], v[46:47], 0, v[232:233]
	global_load_dwordx4 v[228:231], v[234:235], off
	v_mov_b32_e32 v65, s0
	s_mov_b32 s11, s99
	v_mov_b32_e32 v73, s0
	s_waitcnt lgkmcnt(0)
	v_lshlrev_b32_e32 v74, 16, v60
	v_and_b32_e32 v75, 0xffff0000, v60
	v_lshlrev_b32_e32 v60, 16, v61
	v_and_b32_e32 v61, 0xffff0000, v61
	v_pk_mul_f32 v[18:19], v[18:19], v[66:67] op_sel_hi:[1,0]
	v_pk_mul_f32 v[20:21], v[20:21], v[66:67] op_sel_hi:[1,0]
	v_pk_mul_f32 v[2:3], v[2:3], v[66:67] op_sel_hi:[1,0]
	v_pk_mul_f32 v[4:5], v[4:5], v[66:67] op_sel_hi:[1,0]
	v_cvt_pk_bf16_f32 v18, v18, v19
	v_cvt_pk_bf16_f32 v19, v20, v21
	v_pk_mul_f32 v[20:21], v[22:23], v[66:67] op_sel_hi:[1,0]
	v_pk_mul_f32 v[22:23], v[24:25], v[66:67] op_sel_hi:[1,0]
	v_cvt_pk_bf16_f32 v2, v2, v3
	v_cvt_pk_bf16_f32 v3, v4, v5
	v_pk_mul_f32 v[4:5], v[6:7], v[66:67] op_sel_hi:[1,0]
	v_pk_mul_f32 v[6:7], v[8:9], v[66:67] op_sel_hi:[1,0]
	v_cvt_pk_bf16_f32 v20, v20, v21
	v_cvt_pk_bf16_f32 v21, v22, v23
	v_cvt_pk_bf16_f32 v4, v4, v5
	v_cvt_pk_bf16_f32 v5, v6, v7
	v_pk_mul_f32 v[22:23], v[32:33], v[66:67] op_sel_hi:[1,0]
	v_pk_mul_f32 v[6:7], v[16:17], v[66:67] op_sel_hi:[1,0]
	s_waitcnt vmcnt(0)
	v_lshlrev_b32_e32 v76, 16, v50
	v_and_b32_e32 v77, 0xffff0000, v50
	v_mul_f32_e32 v55, 0xbfb8aa3b, v76
	v_mul_f32_e32 v57, 0xbfb8aa3b, v77
	v_exp_f32_e32 v55, v55
	v_exp_f32_e32 v57, v57
	v_lshlrev_b32_e32 v50, 16, v51
	v_and_b32_e32 v51, 0xffff0000, v51
	v_add_f32_e32 v55, 1.0, v55
	v_add_f32_e32 v57, 1.0, v57
	v_rcp_f32_e32 v78, v55
	v_rcp_f32_e32 v79, v57
	v_mul_f32_e32 v55, 0xbfb8aa3b, v51
	v_mul_f32_e32 v59, 0xbfb8aa3b, v50
	v_exp_f32_e32 v55, v55
	v_exp_f32_e32 v59, v59
	v_pk_mul_f32 v[76:77], v[78:79], v[76:77]
	v_add_f32_e32 v55, 1.0, v55
	v_pk_mul_f32 v[74:75], v[76:77], v[74:75]
	v_lshlrev_b32_e32 v76, 16, v52
	v_and_b32_e32 v77, 0xffff0000, v52
	v_mul_f32_e32 v52, 0xbfb8aa3b, v76
	v_add_f32_e32 v57, 1.0, v59
	v_rcp_f32_e32 v79, v55
	v_exp_f32_e32 v52, v52
	v_mul_f32_e32 v55, 0xbfb8aa3b, v77
	v_rcp_f32_e32 v78, v57
	v_exp_f32_e32 v55, v55
	v_add_f32_e32 v52, 1.0, v52
	v_pk_mul_f32 v[50:51], v[78:79], v[50:51]
	v_rcp_f32_e32 v78, v52
	v_add_f32_e32 v52, 1.0, v55
	v_rcp_f32_e32 v79, v52
	v_lshlrev_b32_e32 v52, 16, v53
	v_and_b32_e32 v53, 0xffff0000, v53
	v_mul_f32_e32 v55, 0xbfb8aa3b, v52
	v_exp_f32_e32 v55, v55
	v_mul_f32_e32 v57, 0xbfb8aa3b, v53
	v_exp_f32_e32 v57, v57
	v_pk_mul_f32 v[76:77], v[78:79], v[76:77]
	v_add_f32_e32 v55, 1.0, v55
	v_rcp_f32_e32 v78, v55
	v_add_f32_e32 v55, 1.0, v57
	v_rcp_f32_e32 v79, v55
	v_pk_mul_f32 v[50:51], v[50:51], v[60:61]
	v_lshlrev_b32_e32 v60, 16, v62
	v_and_b32_e32 v61, 0xffff0000, v62
	v_pk_mul_f32 v[76:77], v[76:77], v[60:61]
	v_lshlrev_b32_e32 v60, 16, v63
	v_and_b32_e32 v61, 0xffff0000, v63
	v_pk_mul_f32 v[52:53], v[78:79], v[52:53]
	v_cvt_pk_bf16_f32 v62, v76, v77
	v_pk_mul_f32 v[52:53], v[52:53], v[60:61]
	v_cvt_pk_bf16_f32 v61, v50, v51
	v_lshlrev_b64 v[50:51], 12, v[64:65]
	v_lshlrev_b32_e32 v64, 16, v68
	v_cvt_pk_bf16_f32 v63, v52, v53
	v_and_b32_e32 v65, 0xffff0000, v68
	v_mul_f32_e32 v53, 0xbfb8aa3b, v64
	v_exp_f32_e32 v55, v53
	v_mul_f32_e32 v53, 0xbfb8aa3b, v65
	v_exp_f32_e32 v57, v53
	v_cvt_pk_bf16_f32 v60, v74, v75
	v_add_f32_e32 v55, 1.0, v55
	v_rcp_f32_e32 v74, v55
	v_add_f32_e32 v55, 1.0, v57
	v_lshlrev_b32_e32 v68, 16, v69
	v_rcp_f32_e32 v75, v55
	v_and_b32_e32 v69, 0xffff0000, v69
	v_mul_f32_e32 v55, 0xbfb8aa3b, v68
	v_lshl_add_u64 v[50:51], s[90:91], 0, v[50:51]
	v_exp_f32_e32 v55, v55
	v_mul_f32_e32 v57, 0xbfb8aa3b, v69
	v_lshl_add_u64 v[50:51], v[50:51], 0, s[10:11]
	v_exp_f32_e32 v57, v57
	v_lshl_add_u64 v[50:51], v[50:51], 0, v[0:1]
	flat_store_dwordx4 v[50:51], v[60:63] offset:3072
	ds_read_b128 v[60:63], v58 offset:1152
	v_add_f32_e32 v55, 1.0, v55
	v_pk_mul_f32 v[64:65], v[74:75], v[64:65]
	v_rcp_f32_e32 v74, v55
	v_add_f32_e32 v55, 1.0, v57
	v_rcp_f32_e32 v75, v55
	s_waitcnt lgkmcnt(0)
	v_lshlrev_b32_e32 v52, 16, v60
	v_and_b32_e32 v53, 0xffff0000, v60
	v_pk_mul_f32 v[52:53], v[64:65], v[52:53]
	v_pk_mul_f32 v[64:65], v[74:75], v[68:69]
	v_lshlrev_b32_e32 v68, 16, v70
	v_and_b32_e32 v69, 0xffff0000, v70
	v_mul_f32_e32 v55, 0xbfb8aa3b, v68
	v_exp_f32_e32 v55, v55
	v_mul_f32_e32 v57, 0xbfb8aa3b, v69
	v_exp_f32_e32 v57, v57
	v_lshlrev_b32_e32 v70, 16, v71
	v_add_f32_e32 v55, 1.0, v55
	v_rcp_f32_e32 v74, v55
	v_add_f32_e32 v55, 1.0, v57
	v_rcp_f32_e32 v75, v55
	v_and_b32_e32 v71, 0xffff0000, v71
	v_mul_f32_e32 v55, 0xbfb8aa3b, v70
	v_exp_f32_e32 v55, v55
	v_mul_f32_e32 v57, 0xbfb8aa3b, v71
	v_exp_f32_e32 v57, v57
	v_pk_mul_f32 v[68:69], v[74:75], v[68:69]
	v_add_f32_e32 v55, 1.0, v55
	v_rcp_f32_e32 v74, v55
	v_add_f32_e32 v55, 1.0, v57
	v_rcp_f32_e32 v75, v55
	v_lshlrev_b32_e32 v60, 16, v61
	v_and_b32_e32 v61, 0xffff0000, v61
	v_pk_mul_f32 v[64:65], v[64:65], v[60:61]
	v_lshlrev_b32_e32 v60, 16, v62
	v_and_b32_e32 v61, 0xffff0000, v62
	v_pk_mul_f32 v[68:69], v[68:69], v[60:61]
	v_lshlrev_b32_e32 v60, 16, v63
	v_and_b32_e32 v61, 0xffff0000, v63
	v_pk_mul_f32 v[62:63], v[74:75], v[70:71]
	v_mov_b32_e32 v57, s0
	v_pk_mul_f32 v[70:71], v[62:63], v[60:61]
	v_cvt_pk_bf16_f32 v62, v68, v69
	v_lshlrev_b32_e32 v68, 16, v38
	v_and_b32_e32 v69, 0xffff0000, v38
	v_mul_f32_e32 v38, 0xbfb8aa3b, v68
	v_exp_f32_e32 v38, v38
	v_mul_f32_e32 v55, 0xbfb8aa3b, v69
	v_cvt_pk_bf16_f32 v60, v52, v53
	v_lshlrev_b64 v[52:53], 12, v[72:73]
	v_exp_f32_e32 v55, v55
	v_lshl_add_u64 v[52:53], s[90:91], 0, v[52:53]
	v_lshl_add_u64 v[52:53], v[52:53], 0, s[10:11]
	v_cvt_pk_bf16_f32 v61, v64, v65
	v_cvt_pk_bf16_f32 v63, v70, v71
	v_lshl_add_u64 v[52:53], v[52:53], 0, v[0:1]
	v_add_f32_e32 v38, 1.0, v38
	flat_store_dwordx4 v[52:53], v[60:63] offset:3072
	v_rcp_f32_e32 v70, v38
	v_add_f32_e32 v38, 1.0, v55
	ds_read_b128 v[60:63], v58 offset:2304
	v_rcp_f32_e32 v71, v38
	v_lshlrev_b32_e32 v38, 16, v39
	v_and_b32_e32 v39, 0xffff0000, v39
	v_mul_f32_e32 v55, 0xbfb8aa3b, v38
	v_exp_f32_e32 v55, v55
	v_mul_f32_e32 v59, 0xbfb8aa3b, v39
	v_exp_f32_e32 v59, v59
	s_waitcnt lgkmcnt(0)
	v_lshlrev_b32_e32 v64, 16, v60
	v_and_b32_e32 v65, 0xffff0000, v60
	v_pk_mul_f32 v[68:69], v[70:71], v[68:69]
	v_add_f32_e32 v55, 1.0, v55
	v_pk_mul_f32 v[64:65], v[68:69], v[64:65]
	v_lshlrev_b32_e32 v68, 16, v40
	v_rcp_f32_e32 v70, v55
	v_add_f32_e32 v55, 1.0, v59
	v_and_b32_e32 v69, 0xffff0000, v40
	v_mul_f32_e32 v40, 0xbfb8aa3b, v68
	v_rcp_f32_e32 v71, v55
	v_exp_f32_e32 v40, v40
	v_mul_f32_e32 v55, 0xbfb8aa3b, v69
	v_exp_f32_e32 v55, v55
	v_pk_mul_f32 v[38:39], v[70:71], v[38:39]
	v_add_f32_e32 v40, 1.0, v40
	v_rcp_f32_e32 v70, v40
	v_add_f32_e32 v40, 1.0, v55
	v_rcp_f32_e32 v71, v40
	v_lshlrev_b32_e32 v40, 16, v41
	v_and_b32_e32 v41, 0xffff0000, v41
	v_mul_f32_e32 v55, 0xbfb8aa3b, v40
	v_exp_f32_e32 v55, v55
	v_mul_f32_e32 v59, 0xbfb8aa3b, v41
	v_exp_f32_e32 v59, v59
	v_pk_mul_f32 v[68:69], v[70:71], v[68:69]
	v_add_f32_e32 v55, 1.0, v55
	v_rcp_f32_e32 v70, v55
	v_add_f32_e32 v55, 1.0, v59
	v_rcp_f32_e32 v71, v55
	v_lshlrev_b32_e32 v60, 16, v61
	v_and_b32_e32 v61, 0xffff0000, v61
	v_pk_mul_f32 v[38:39], v[38:39], v[60:61]
	v_lshlrev_b32_e32 v60, 16, v62
	v_and_b32_e32 v61, 0xffff0000, v62
	v_pk_mul_f32 v[68:69], v[68:69], v[60:61]
	v_lshlrev_b32_e32 v60, 16, v63
	v_and_b32_e32 v61, 0xffff0000, v63
	v_pk_mul_f32 v[40:41], v[70:71], v[40:41]
	v_cvt_pk_bf16_f32 v62, v68, v69
	v_pk_mul_f32 v[40:41], v[40:41], v[60:61]
	v_cvt_pk_bf16_f32 v61, v38, v39
	v_lshlrev_b64 v[38:39], 12, v[56:57]
	v_lshlrev_b32_e32 v56, 16, v34
	v_lshl_add_u64 v[38:39], s[90:91], 0, v[38:39]
	v_and_b32_e32 v57, 0xffff0000, v34
	v_mul_f32_e32 v34, 0xbfb8aa3b, v56
	v_cvt_pk_bf16_f32 v63, v40, v41
	v_lshl_add_u64 v[38:39], v[38:39], 0, s[10:11]
	v_exp_f32_e32 v34, v34
	v_mul_f32_e32 v41, 0xbfb8aa3b, v57
	v_cvt_pk_bf16_f32 v60, v64, v65
	v_lshl_add_u64 v[38:39], v[38:39], 0, v[0:1]
	v_exp_f32_e32 v59, v41
	flat_store_dwordx4 v[38:39], v[60:63] offset:3072
	ds_read_b128 v[60:63], v58 offset:3456
	v_add_f32_e32 v34, 1.0, v34
	v_rcp_f32_e32 v64, v34
	v_add_f32_e32 v34, 1.0, v59
	v_rcp_f32_e32 v65, v34
	v_lshlrev_b32_e32 v34, 16, v35
	v_and_b32_e32 v35, 0xffff0000, v35
	v_mul_f32_e32 v59, 0xbfb8aa3b, v34
	s_waitcnt lgkmcnt(0)
	v_lshlrev_b32_e32 v40, 16, v60
	v_and_b32_e32 v41, 0xffff0000, v60
	v_exp_f32_e32 v59, v59
	v_mul_f32_e32 v60, 0xbfb8aa3b, v35
	v_exp_f32_e32 v60, v60
	v_pk_mul_f32 v[56:57], v[64:65], v[56:57]
	v_add_f32_e32 v59, 1.0, v59
	v_rcp_f32_e32 v64, v59
	v_add_f32_e32 v59, 1.0, v60
	v_rcp_f32_e32 v65, v59
	v_lshlrev_b32_e32 v60, 16, v36
	v_pk_mul_f32 v[40:41], v[56:57], v[40:41]
	v_lshlrev_b32_e32 v56, 16, v61
	v_and_b32_e32 v57, 0xffff0000, v61
	v_pk_mul_f32 v[34:35], v[64:65], v[34:35]
	v_and_b32_e32 v61, 0xffff0000, v36
	v_mul_f32_e32 v36, 0xbfb8aa3b, v60
	v_pk_mul_f32 v[34:35], v[34:35], v[56:57]
	v_exp_f32_e32 v36, v36
	v_mul_f32_e32 v57, 0xbfb8aa3b, v61
	v_exp_f32_e32 v59, v57
	v_lshlrev_b32_e32 v56, 16, v62
	v_add_f32_e32 v36, 1.0, v36
	v_rcp_f32_e32 v64, v36
	v_add_f32_e32 v36, 1.0, v59
	v_rcp_f32_e32 v65, v36
	v_lshlrev_b32_e32 v36, 16, v37
	v_and_b32_e32 v37, 0xffff0000, v37
	v_mul_f32_e32 v59, 0xbfb8aa3b, v36
	v_and_b32_e32 v57, 0xffff0000, v62
	v_exp_f32_e32 v59, v59
	v_mul_f32_e32 v62, 0xbfb8aa3b, v37
	v_exp_f32_e32 v62, v62
	v_pk_mul_f32 v[60:61], v[64:65], v[60:61]
	v_add_f32_e32 v59, 1.0, v59
	v_rcp_f32_e32 v64, v59
	v_add_f32_e32 v59, 1.0, v62
	v_rcp_f32_e32 v65, v59
	v_mov_b32_e32 v55, s0
	v_pk_mul_f32 v[56:57], v[60:61], v[56:57]
	v_lshlrev_b32_e32 v60, 16, v63
	v_and_b32_e32 v61, 0xffff0000, v63
	v_pk_mul_f32 v[36:37], v[64:65], v[36:37]
	v_cvt_pk_bf16_f32 v62, v56, v57
	v_pk_mul_f32 v[36:37], v[36:37], v[60:61]
	v_cvt_pk_bf16_f32 v61, v34, v35
	v_lshlrev_b64 v[34:35], 12, v[54:55]
	v_lshl_add_u64 v[34:35], s[90:91], 0, v[34:35]
	v_lshl_add_u64 v[34:35], v[34:35], 0, s[10:11]
	v_cvt_pk_bf16_f32 v60, v40, v41
	v_cvt_pk_bf16_f32 v63, v36, v37
	v_lshl_add_u64 v[36:37], v[34:35], 0, v[0:1]
	flat_store_dwordx4 v[36:37], v[60:63] offset:3072
	ds_write2_b64 v197, v[18:19], v[20:21] offset1:2
	v_pk_mul_f32 v[18:19], v[26:27], v[66:67] op_sel_hi:[1,0]
	v_pk_mul_f32 v[20:21], v[28:29], v[66:67] op_sel_hi:[1,0]
	ds_write2_b64 v197, v[2:3], v[4:5] offset0:8 offset1:10
	v_pk_mul_f32 v[2:3], v[10:11], v[66:67] op_sel_hi:[1,0]
	v_pk_mul_f32 v[4:5], v[12:13], v[66:67] op_sel_hi:[1,0]
	v_cvt_pk_bf16_f32 v18, v18, v19
	v_cvt_pk_bf16_f32 v19, v20, v21
	v_pk_mul_f32 v[20:21], v[30:31], v[66:67] op_sel_hi:[1,0]
	v_cvt_pk_bf16_f32 v2, v2, v3
	v_cvt_pk_bf16_f32 v3, v4, v5
	v_pk_mul_f32 v[4:5], v[14:15], v[66:67] op_sel_hi:[1,0]
	v_cvt_pk_bf16_f32 v20, v20, v21
	v_cvt_pk_bf16_f32 v21, v22, v23
	v_cvt_pk_bf16_f32 v4, v4, v5
	v_cvt_pk_bf16_f32 v5, v6, v7
	ds_write2_b64 v197, v[18:19], v[20:21] offset0:4 offset1:6
	ds_write2_b64 v197, v[2:3], v[4:5] offset0:12 offset1:14
	v_lshlrev_b32_e32 v0, 1, v174
	s_waitcnt lgkmcnt(0)
	v_lshl_add_u64 v[2:3], v[42:43], 0, v[0:1]
	v_mov_b32_e32 v10, v216
	v_mov_b32_e32 v11, v217
	v_mov_b32_e32 v12, v218
	v_mov_b32_e32 v13, v219
	v_lshl_add_u64 v[2:3], v[48:49], 0, v[0:1]
	v_mov_b32_e32 v14, v220
	v_mov_b32_e32 v15, v221
	v_mov_b32_e32 v16, v222
	v_mov_b32_e32 v17, v223
	v_lshl_add_u64 v[2:3], v[44:45], 0, v[0:1]
	v_lshl_add_u64 v[4:5], v[46:47], 0, v[0:1]
	ds_read_b128 v[18:21], v58
	v_mov_b32_e32 v6, v224
	v_mov_b32_e32 v7, v225
	v_mov_b32_e32 v8, v226
	v_mov_b32_e32 v9, v227
	s_nop 0
	v_mov_b32_e32 v2, v228
	v_mov_b32_e32 v3, v229
	v_mov_b32_e32 v4, v230
	v_mov_b32_e32 v5, v231
	s_mov_b64 s[0:1], 0xc00
	v_lshl_add_u64 v[48:49], v[34:35], 0, s[0:1]
	s_waitcnt lgkmcnt(0)
	v_lshlrev_b32_e32 v22, 16, v18
	v_and_b32_e32 v23, 0xffff0000, v18
	s_waitcnt vmcnt(4)
	v_lshlrev_b32_e32 v24, 16, v10
	v_and_b32_e32 v25, 0xffff0000, v10
	v_mul_f32_e32 v0, 0xbfb8aa3b, v24
	v_exp_f32_e32 v0, v0
	v_mul_f32_e32 v10, 0xbfb8aa3b, v25
	v_exp_f32_e32 v10, v10
	v_add_f32_e32 v0, 1.0, v0
	v_rcp_f32_e32 v26, v0
	v_add_f32_e32 v0, 1.0, v10
	v_lshlrev_b32_e32 v10, 16, v11
	v_rcp_f32_e32 v27, v0
	v_and_b32_e32 v11, 0xffff0000, v11
	v_mul_f32_e32 v0, 0xbfb8aa3b, v10
	v_exp_f32_e32 v0, v0
	v_mul_f32_e32 v18, 0xbfb8aa3b, v11
	v_exp_f32_e32 v18, v18
	v_pk_mul_f32 v[24:25], v[26:27], v[24:25]
	v_add_f32_e32 v0, 1.0, v0
	v_rcp_f32_e32 v26, v0
	v_add_f32_e32 v0, 1.0, v18
	v_rcp_f32_e32 v27, v0
	v_pk_mul_f32 v[22:23], v[24:25], v[22:23]
	v_lshlrev_b32_e32 v24, 16, v12
	v_lshlrev_b32_e32 v18, 16, v19
	v_and_b32_e32 v19, 0xffff0000, v19
	v_pk_mul_f32 v[10:11], v[26:27], v[10:11]
	v_and_b32_e32 v25, 0xffff0000, v12
	v_mul_f32_e32 v0, 0xbfb8aa3b, v24
	v_pk_mul_f32 v[18:19], v[10:11], v[18:19]
	v_exp_f32_e32 v0, v0
	v_mul_f32_e32 v11, 0xbfb8aa3b, v25
	v_exp_f32_e32 v12, v11
	v_lshlrev_b32_e32 v10, 16, v20
	v_add_f32_e32 v0, 1.0, v0
	v_rcp_f32_e32 v26, v0
	v_add_f32_e32 v0, 1.0, v12
	v_lshlrev_b32_e32 v12, 16, v13
	v_rcp_f32_e32 v27, v0
	v_and_b32_e32 v13, 0xffff0000, v13
	v_mul_f32_e32 v0, 0xbfb8aa3b, v12
	v_and_b32_e32 v11, 0xffff0000, v20
	v_exp_f32_e32 v0, v0
	v_mul_f32_e32 v20, 0xbfb8aa3b, v13
	v_exp_f32_e32 v20, v20
	v_pk_mul_f32 v[24:25], v[26:27], v[24:25]
	v_add_f32_e32 v0, 1.0, v0
	v_rcp_f32_e32 v26, v0
	v_add_f32_e32 v0, 1.0, v20
	v_rcp_f32_e32 v27, v0
	v_pk_mul_f32 v[24:25], v[24:25], v[10:11]
	v_lshlrev_b32_e32 v10, 16, v21
	v_and_b32_e32 v11, 0xffff0000, v21
	v_pk_mul_f32 v[12:13], v[26:27], v[12:13]
	s_nop 0
	v_pk_mul_f32 v[20:21], v[12:13], v[10:11]
	v_cvt_pk_bf16_f32 v10, v22, v23
	v_cvt_pk_bf16_f32 v13, v20, v21
	v_lshlrev_b32_e32 v20, 16, v14
	v_and_b32_e32 v21, 0xffff0000, v14
	v_mul_f32_e32 v0, 0xbfb8aa3b, v20
	v_cvt_pk_bf16_f32 v11, v18, v19
	v_cvt_pk_bf16_f32 v12, v24, v25
	v_exp_f32_e32 v0, v0
	v_mul_f32_e32 v14, 0xbfb8aa3b, v21
	flat_store_dwordx4 v[50:51], v[10:13] offset:3200
	v_exp_f32_e32 v14, v14
	ds_read_b128 v[10:13], v58 offset:1152
	v_add_f32_e32 v0, 1.0, v0
	v_rcp_f32_e32 v22, v0
	v_add_f32_e32 v0, 1.0, v14
	v_lshlrev_b32_e32 v14, 16, v15
	v_rcp_f32_e32 v23, v0
	v_and_b32_e32 v15, 0xffff0000, v15
	v_mul_f32_e32 v0, 0xbfb8aa3b, v14
	s_waitcnt lgkmcnt(0)
	v_lshlrev_b32_e32 v18, 16, v10
	v_and_b32_e32 v19, 0xffff0000, v10
	v_exp_f32_e32 v0, v0
	v_mul_f32_e32 v10, 0xbfb8aa3b, v15
	v_exp_f32_e32 v10, v10
	v_pk_mul_f32 v[20:21], v[22:23], v[20:21]
	v_add_f32_e32 v0, 1.0, v0
	v_rcp_f32_e32 v22, v0
	v_add_f32_e32 v0, 1.0, v10
	v_rcp_f32_e32 v23, v0
	v_pk_mul_f32 v[18:19], v[20:21], v[18:19]
	v_lshlrev_b32_e32 v20, 16, v16
	v_lshlrev_b32_e32 v10, 16, v11
	v_and_b32_e32 v11, 0xffff0000, v11
	v_pk_mul_f32 v[14:15], v[22:23], v[14:15]
	v_and_b32_e32 v21, 0xffff0000, v16
	v_mul_f32_e32 v0, 0xbfb8aa3b, v20
	v_pk_mul_f32 v[14:15], v[14:15], v[10:11]
	v_exp_f32_e32 v0, v0
	v_mul_f32_e32 v11, 0xbfb8aa3b, v21
	v_exp_f32_e32 v16, v11
	v_lshlrev_b32_e32 v10, 16, v12
	v_add_f32_e32 v0, 1.0, v0
	v_rcp_f32_e32 v22, v0
	v_add_f32_e32 v0, 1.0, v16
	v_lshlrev_b32_e32 v16, 16, v17
	v_rcp_f32_e32 v23, v0
	v_and_b32_e32 v17, 0xffff0000, v17
	v_mul_f32_e32 v0, 0xbfb8aa3b, v16
	v_and_b32_e32 v11, 0xffff0000, v12
	v_exp_f32_e32 v0, v0
	v_mul_f32_e32 v12, 0xbfb8aa3b, v17
	v_exp_f32_e32 v12, v12
	v_pk_mul_f32 v[20:21], v[22:23], v[20:21]
	v_add_f32_e32 v0, 1.0, v0
	v_rcp_f32_e32 v22, v0
	v_add_f32_e32 v0, 1.0, v12
	v_rcp_f32_e32 v23, v0
	v_pk_mul_f32 v[20:21], v[20:21], v[10:11]
	v_lshlrev_b32_e32 v10, 16, v13
	v_and_b32_e32 v11, 0xffff0000, v13
	v_pk_mul_f32 v[12:13], v[22:23], v[16:17]
	s_nop 0
	v_pk_mul_f32 v[16:17], v[12:13], v[10:11]
	v_cvt_pk_bf16_f32 v10, v18, v19
	v_cvt_pk_bf16_f32 v13, v16, v17
	v_lshlrev_b32_e32 v16, 16, v6
	v_and_b32_e32 v17, 0xffff0000, v6
	v_mul_f32_e32 v0, 0xbfb8aa3b, v16
	v_cvt_pk_bf16_f32 v11, v14, v15
	v_cvt_pk_bf16_f32 v12, v20, v21
	v_exp_f32_e32 v0, v0
	v_mul_f32_e32 v6, 0xbfb8aa3b, v17
	flat_store_dwordx4 v[52:53], v[10:13] offset:3200
	v_exp_f32_e32 v6, v6
	ds_read_b128 v[10:13], v58 offset:2304
	v_add_f32_e32 v0, 1.0, v0
	v_rcp_f32_e32 v18, v0
	v_add_f32_e32 v0, 1.0, v6
	v_lshlrev_b32_e32 v6, 16, v7
	v_rcp_f32_e32 v19, v0
	v_and_b32_e32 v7, 0xffff0000, v7
	v_mul_f32_e32 v0, 0xbfb8aa3b, v6
	s_waitcnt lgkmcnt(0)
	v_lshlrev_b32_e32 v14, 16, v10
	v_and_b32_e32 v15, 0xffff0000, v10
	v_exp_f32_e32 v0, v0
	v_mul_f32_e32 v10, 0xbfb8aa3b, v7
	v_exp_f32_e32 v10, v10
	v_pk_mul_f32 v[16:17], v[18:19], v[16:17]
	v_add_f32_e32 v0, 1.0, v0
	v_rcp_f32_e32 v18, v0
	v_add_f32_e32 v0, 1.0, v10
	v_rcp_f32_e32 v19, v0
	v_pk_mul_f32 v[14:15], v[16:17], v[14:15]
	v_lshlrev_b32_e32 v16, 16, v8
	v_lshlrev_b32_e32 v10, 16, v11
	v_and_b32_e32 v11, 0xffff0000, v11
	v_pk_mul_f32 v[6:7], v[18:19], v[6:7]
	v_and_b32_e32 v17, 0xffff0000, v8
	v_mul_f32_e32 v0, 0xbfb8aa3b, v16
	v_pk_mul_f32 v[10:11], v[6:7], v[10:11]
	v_exp_f32_e32 v0, v0
	v_mul_f32_e32 v7, 0xbfb8aa3b, v17
	v_exp_f32_e32 v8, v7
	v_lshlrev_b32_e32 v6, 16, v12
	v_add_f32_e32 v0, 1.0, v0
	v_rcp_f32_e32 v18, v0
	v_add_f32_e32 v0, 1.0, v8
	v_lshlrev_b32_e32 v8, 16, v9
	v_rcp_f32_e32 v19, v0
	v_and_b32_e32 v9, 0xffff0000, v9
	v_mul_f32_e32 v0, 0xbfb8aa3b, v8
	v_and_b32_e32 v7, 0xffff0000, v12
	v_exp_f32_e32 v0, v0
	v_mul_f32_e32 v12, 0xbfb8aa3b, v9
	v_exp_f32_e32 v12, v12
	v_pk_mul_f32 v[16:17], v[18:19], v[16:17]
	v_add_f32_e32 v0, 1.0, v0
	v_rcp_f32_e32 v18, v0
	v_add_f32_e32 v0, 1.0, v12
	v_rcp_f32_e32 v19, v0
	v_pk_mul_f32 v[16:17], v[16:17], v[6:7]
	v_lshlrev_b32_e32 v6, 16, v13
	v_and_b32_e32 v7, 0xffff0000, v13
	v_pk_mul_f32 v[8:9], v[18:19], v[8:9]
	s_nop 0
	v_pk_mul_f32 v[12:13], v[8:9], v[6:7]
	v_cvt_pk_bf16_f32 v6, v14, v15
	v_cvt_pk_bf16_f32 v9, v12, v13
	v_lshlrev_b32_e32 v12, 16, v2
	v_and_b32_e32 v13, 0xffff0000, v2
	v_mul_f32_e32 v0, 0xbfb8aa3b, v12
	v_cvt_pk_bf16_f32 v7, v10, v11
	v_cvt_pk_bf16_f32 v8, v16, v17
	v_exp_f32_e32 v0, v0
	v_mul_f32_e32 v2, 0xbfb8aa3b, v13
	flat_store_dwordx4 v[38:39], v[6:9] offset:3200
	v_exp_f32_e32 v2, v2
	ds_read_b128 v[6:9], v58 offset:3456
	v_add_f32_e32 v0, 1.0, v0
	v_rcp_f32_e32 v14, v0
	v_add_f32_e32 v0, 1.0, v2
	v_lshlrev_b32_e32 v2, 16, v3
	v_rcp_f32_e32 v15, v0
	v_and_b32_e32 v3, 0xffff0000, v3
	v_mul_f32_e32 v0, 0xbfb8aa3b, v2
	s_waitcnt lgkmcnt(0)
	v_lshlrev_b32_e32 v10, 16, v6
	v_and_b32_e32 v11, 0xffff0000, v6
	v_exp_f32_e32 v0, v0
	v_mul_f32_e32 v6, 0xbfb8aa3b, v3
	v_exp_f32_e32 v6, v6
	v_pk_mul_f32 v[12:13], v[14:15], v[12:13]
	v_add_f32_e32 v0, 1.0, v0
	v_rcp_f32_e32 v14, v0
	v_add_f32_e32 v0, 1.0, v6
	v_rcp_f32_e32 v15, v0
	v_pk_mul_f32 v[10:11], v[12:13], v[10:11]
	v_lshlrev_b32_e32 v12, 16, v4
	v_lshlrev_b32_e32 v6, 16, v7
	v_and_b32_e32 v7, 0xffff0000, v7
	v_pk_mul_f32 v[2:3], v[14:15], v[2:3]
	v_and_b32_e32 v13, 0xffff0000, v4
	v_mul_f32_e32 v0, 0xbfb8aa3b, v12
	v_pk_mul_f32 v[6:7], v[2:3], v[6:7]
	v_exp_f32_e32 v0, v0
	v_mul_f32_e32 v3, 0xbfb8aa3b, v13
	v_exp_f32_e32 v4, v3
	v_lshlrev_b32_e32 v2, 16, v8
	v_add_f32_e32 v0, 1.0, v0
	v_rcp_f32_e32 v14, v0
	v_add_f32_e32 v0, 1.0, v4
	v_lshlrev_b32_e32 v4, 16, v5
	v_rcp_f32_e32 v15, v0
	v_and_b32_e32 v5, 0xffff0000, v5
	v_mul_f32_e32 v0, 0xbfb8aa3b, v4
	v_and_b32_e32 v3, 0xffff0000, v8
	v_exp_f32_e32 v0, v0
	v_mul_f32_e32 v8, 0xbfb8aa3b, v5
	v_exp_f32_e32 v8, v8
	v_pk_mul_f32 v[12:13], v[14:15], v[12:13]
	v_add_f32_e32 v0, 1.0, v0
	v_rcp_f32_e32 v14, v0
	v_add_f32_e32 v0, 1.0, v8
	v_rcp_f32_e32 v15, v0
	v_pk_mul_f32 v[12:13], v[12:13], v[2:3]
	v_lshlrev_b32_e32 v2, 16, v9
	v_and_b32_e32 v3, 0xffff0000, v9
	v_pk_mul_f32 v[4:5], v[14:15], v[4:5]
	s_nop 0
	v_pk_mul_f32 v[8:9], v[4:5], v[2:3]
	v_cvt_pk_bf16_f32 v2, v10, v11
	v_cvt_pk_bf16_f32 v3, v6, v7
	v_cvt_pk_bf16_f32 v4, v12, v13
	v_cvt_pk_bf16_f32 v5, v8, v9
	s_cbranch_execnz .LBB0_624

.LBB0_565:
	s_add_i32 s0, s19, -4
	v_cmp_ge_u32_e32 vcc, s0, v130
	v_cmp_lt_u32_e64 s[12:13], s0, v129
	s_and_b64 s[0:1], vcc, s[12:13]
	s_andn2_b64 vcc, exec, s[0:1]
	s_cbranch_vccnz .LBB0_602
	s_lshl_b32 s0, s64, 14
	s_add_i32 s1, s64, 1
	s_cmp_lg_u32 s1, 6
	s_cselect_b32 s1, s1, 0
	s_lshl_b32 s1, s1, 14
	v_add_u32_e32 v251, s0, v248
	v_xor_b32_e32 v0, 32, v251
	v_xor_b32_e32 v2, 64, v251
	ds_read_b128 v[4:7], v251
	ds_read_b128 v[8:11], v0
	v_xor_b32_e32 v0, 0x60, v251
	ds_read_b128 v[12:15], v2
	v_xor_b32_e32 v2, 0x80, v251
	ds_read_b128 v[134:137], v0
	v_xor_b32_e32 v0, 0xa0, v251
	ds_read_b128 v[138:141], v2
	v_xor_b32_e32 v2, 0xc0, v251
	ds_read_b128 v[142:145], v0
	v_xor_b32_e32 v0, 0xe0, v251
	ds_read_b128 v[198:201], v2
	ds_read_b128 v[216:219], v0
	ds_read2_b32 v[232:233], v131 offset1:1
	ds_read2_b32 v[234:235], v131 offset0:2 offset1:3
	ds_read2_b32 v[236:237], v131 offset0:8 offset1:9
	ds_read2_b32 v[238:239], v131 offset0:10 offset1:11
	ds_read2_b32 v[240:241], v131 offset0:16 offset1:17
	ds_read2_b32 v[242:243], v131 offset0:18 offset1:19
	ds_read2_b32 v[244:245], v131 offset0:24 offset1:25
	s_waitcnt lgkmcnt(14)
	v_mfma_f32_32x32x16_bf16 v[80:95], v[4:7], v[124:127], 0
	ds_read2_b32 v[246:247], v131 offset0:26 offset1:27
	v_add_u32_e32 v0, s19, v132
	v_cmp_gt_u32_e32 vcc, 8, v0
	v_add_u32_e32 v2, s1, v249
	v_add_u32_e32 v3, s1, v250
	v_cndmask_b32_e32 v0, v212, v187, vcc
	s_waitcnt lgkmcnt(14)
	v_mfma_f32_32x32x16_bf16 v[80:95], v[8:11], v[120:123], v[80:95]
	s_waitcnt lgkmcnt(13)
	v_mfma_f32_32x32x16_bf16 v[80:95], v[12:15], v[116:119], v[80:95]
	s_waitcnt lgkmcnt(12)
	v_mfma_f32_32x32x16_bf16 v[80:95], v[134:137], v[112:115], v[80:95]
	s_waitcnt lgkmcnt(11)
	v_mfma_f32_32x32x16_bf16 v[80:95], v[138:141], v[108:111], v[80:95]
	s_waitcnt lgkmcnt(10)
	v_mfma_f32_32x32x16_bf16 v[80:95], v[142:145], v[104:107], v[80:95]
	s_waitcnt lgkmcnt(9)
	v_mfma_f32_32x32x16_bf16 v[80:95], v[198:201], v[100:103], v[80:95]
	s_waitcnt lgkmcnt(8)
	v_mfma_f32_32x32x16_bf16 v[80:95], v[216:219], v[96:99], v[80:95]
	v_xor_b32_e32 v4, 64, v2
	v_xor_b32_e32 v5, 64, v3
	v_xor_b32_e32 v6, 0x80, v2
	v_xor_b32_e32 v7, 0x80, v3
	v_xor_b32_e32 v8, 0xc0, v2
	v_xor_b32_e32 v9, 0xc0, v3
	ds_read_b64_tr_b16 v[220:221], v2
	ds_read_b64_tr_b16 v[222:223], v3
	ds_read_b64_tr_b16 v[224:225], v4
	ds_read_b64_tr_b16 v[226:227], v5
	ds_read_b64_tr_b16 v[228:229], v6
	ds_read_b64_tr_b16 v[230:231], v7
	ds_read_b64_tr_b16 v[198:199], v8
	ds_read_b64_tr_b16 v[200:201], v9
	s_waitcnt lgkmcnt(8)
	v_cmp_gt_u32_e32 vcc, 16, v0
	v_add_f32_e32 v232, v80, v232
	v_add_u32_e32 v251, 1, v0
	v_cmp_gt_u32_e64 s[0:1], 16, v251
	v_add_f32_e32 v233, v81, v233
	v_cndmask_b32_e32 v80, v210, v232, vcc
	v_add_u32_e32 v251, 2, v0
	v_cmp_gt_u32_e32 vcc, 16, v251
	v_add_f32_e32 v234, v82, v234
	v_cndmask_b32_e64 v81, v210, v233, s[0:1]
	v_add_u32_e32 v251, 3, v0
	v_cmp_gt_u32_e64 s[0:1], 16, v251
	v_add_f32_e32 v235, v83, v235
	v_cndmask_b32_e32 v82, v210, v234, vcc
	v_add_u32_e32 v251, 8, v0
	v_cmp_gt_u32_e32 vcc, 16, v251
	v_add_f32_e32 v236, v84, v236
	v_cndmask_b32_e64 v83, v210, v235, s[0:1]
	v_add_u32_e32 v251, 9, v0
	v_cmp_gt_u32_e64 s[0:1], 16, v251
	v_add_f32_e32 v237, v85, v237
	v_cndmask_b32_e32 v84, v210, v236, vcc
	v_add_u32_e32 v251, 10, v0
	v_cmp_gt_u32_e32 vcc, 16, v251
	v_add_f32_e32 v238, v86, v238
	v_cndmask_b32_e64 v85, v210, v237, s[0:1]
	v_add_u32_e32 v251, 11, v0
	v_cmp_gt_u32_e64 s[0:1], 16, v251
	v_add_f32_e32 v239, v87, v239
	v_cndmask_b32_e32 v86, v210, v238, vcc
	v_add_u32_e32 v251, 16, v0
	v_cmp_gt_u32_e32 vcc, 16, v251
	v_add_f32_e32 v240, v88, v240
	v_cndmask_b32_e64 v87, v210, v239, s[0:1]
	v_add_u32_e32 v251, 17, v0
	v_cmp_gt_u32_e64 s[0:1], 16, v251
	v_add_f32_e32 v241, v89, v241
	v_cndmask_b32_e32 v88, v210, v240, vcc
	v_add_u32_e32 v251, 18, v0
	v_cmp_gt_u32_e32 vcc, 16, v251
	v_add_f32_e32 v242, v90, v242
	v_cndmask_b32_e64 v89, v210, v241, s[0:1]
	v_add_u32_e32 v251, 19, v0
	v_cmp_gt_u32_e64 s[0:1], 16, v251
	v_add_f32_e32 v243, v91, v243
	v_cndmask_b32_e32 v90, v210, v242, vcc
	v_add_u32_e32 v251, 24, v0
	v_cmp_gt_u32_e32 vcc, 16, v251
	v_add_f32_e32 v244, v92, v244
	v_cndmask_b32_e64 v91, v210, v243, s[0:1]
	v_add_u32_e32 v251, 25, v0
	v_cmp_gt_u32_e64 s[0:1], 16, v251
	v_add_f32_e32 v245, v93, v245
	v_cndmask_b32_e32 v92, v210, v244, vcc
	v_add_u32_e32 v251, 26, v0
	v_cmp_gt_u32_e32 vcc, 16, v251
	v_add_f32_e32 v246, v94, v246
	v_cndmask_b32_e64 v93, v210, v245, s[0:1]
	v_add_u32_e32 v251, 27, v0
	v_cmp_gt_u32_e64 s[0:1], 16, v251
	v_add_f32_e32 v247, v95, v247
	v_cndmask_b32_e32 v94, v210, v246, vcc
	s_nop 1
	v_cndmask_b32_e64 v95, v210, v247, s[0:1]
	ds_read_b64_tr_b16 v[232:233], v2 offset:4096
	ds_read_b64_tr_b16 v[234:235], v3 offset:4096
	ds_read_b64_tr_b16 v[236:237], v4 offset:4096
	ds_read_b64_tr_b16 v[238:239], v5 offset:4096
	ds_read_b64_tr_b16 v[240:241], v6 offset:4096
	ds_read_b64_tr_b16 v[242:243], v7 offset:4096
	ds_read_b64_tr_b16 v[244:245], v8 offset:4096
	ds_read_b64_tr_b16 v[246:247], v9 offset:4096
	v_max3_f32 v0, v80, v81, v82
	v_max3_f32 v4, v83, v84, v85
	v_max3_f32 v215, v86, v87, v88
	v_max3_f32 v0, v0, v89, v90
	v_max3_f32 v4, v4, v91, v92
	v_max3_f32 v215, v215, v93, v94
	v_max3_f32 v0, v0, v4, v215
	v_max_f32_e32 v0, v0, v95
	v_mov_b32_e32 v4, v0
	s_nop 1
	v_permlane32_swap_b32_e32 v4, v0
	s_nop 0
	v_max3_f32 v4, v133, v0, v4
	v_sub_f32_e32 v0, v133, v4
	v_exp_f32_e32 v0, v0
	v_sub_f32_e32 v80, v80, v4
	v_sub_f32_e32 v81, v81, v4
	v_exp_f32_e32 v80, v80
	v_sub_f32_e32 v82, v82, v4
	v_exp_f32_e32 v81, v81
	v_sub_f32_e32 v83, v83, v4
	v_exp_f32_e32 v82, v82
	v_sub_f32_e32 v84, v84, v4
	v_add_f32_e32 v215, v81, v80
	v_exp_f32_e32 v83, v83
	v_sub_f32_e32 v85, v85, v4
	v_add_f32_e32 v215, v82, v215
	v_exp_f32_e32 v84, v84
	v_sub_f32_e32 v86, v86, v4
	v_add_f32_e32 v215, v83, v215
	v_exp_f32_e32 v85, v85
	v_sub_f32_e32 v87, v87, v4
	v_add_f32_e32 v215, v84, v215
	v_exp_f32_e32 v86, v86
	v_sub_f32_e32 v88, v88, v4
	v_add_f32_e32 v215, v85, v215
	v_exp_f32_e32 v87, v87
	v_sub_f32_e32 v89, v89, v4
	v_add_f32_e32 v215, v86, v215
	v_exp_f32_e32 v88, v88
	v_sub_f32_e32 v90, v90, v4
	v_add_f32_e32 v215, v87, v215
	v_exp_f32_e32 v89, v89
	v_sub_f32_e32 v91, v91, v4
	v_add_f32_e32 v215, v88, v215
	v_exp_f32_e32 v90, v90
	v_sub_f32_e32 v92, v92, v4
	v_add_f32_e32 v215, v89, v215
	v_exp_f32_e32 v91, v91
	v_sub_f32_e32 v93, v93, v4
	v_add_f32_e32 v215, v90, v215
	v_exp_f32_e32 v92, v92
	v_sub_f32_e32 v94, v94, v4
	v_add_f32_e32 v215, v91, v215
	v_exp_f32_e32 v93, v93
	v_sub_f32_e32 v95, v95, v4
	v_add_f32_e32 v215, v92, v215
	v_exp_f32_e32 v94, v94
	v_add_f32_e32 v215, v93, v215
	v_exp_f32_e32 v95, v95
	v_add_f32_e32 v215, v94, v215
	v_add_f32_e32 v215, v95, v215
	v_fmac_f32_e32 v215, v128, v0
	v_cvt_pk_bf16_f32 v8, v80, v81
	v_cvt_pk_bf16_f32 v9, v82, v83
	v_cvt_pk_bf16_f32 v10, v84, v85
	v_cvt_pk_bf16_f32 v11, v86, v87
	v_cvt_pk_bf16_f32 v12, v88, v89
	v_cvt_pk_bf16_f32 v13, v90, v91
	v_cvt_pk_bf16_f32 v14, v92, v93
	v_cvt_pk_bf16_f32 v15, v94, v95
	s_waitcnt lgkmcnt(8)
	v_pk_mul_f32 v[64:65], v[64:65], v[0:1] op_sel_hi:[1,0]
	v_pk_mul_f32 v[66:67], v[66:67], v[0:1] op_sel_hi:[1,0]
	v_pk_mul_f32 v[68:69], v[68:69], v[0:1] op_sel_hi:[1,0]
	v_pk_mul_f32 v[70:71], v[70:71], v[0:1] op_sel_hi:[1,0]
	v_pk_mul_f32 v[72:73], v[72:73], v[0:1] op_sel_hi:[1,0]
	v_pk_mul_f32 v[74:75], v[74:75], v[0:1] op_sel_hi:[1,0]
	v_pk_mul_f32 v[76:77], v[76:77], v[0:1] op_sel_hi:[1,0]
	v_pk_mul_f32 v[78:79], v[78:79], v[0:1] op_sel_hi:[1,0]
	v_pk_mul_f32 v[48:49], v[48:49], v[0:1] op_sel_hi:[1,0]
	v_pk_mul_f32 v[50:51], v[50:51], v[0:1] op_sel_hi:[1,0]
	v_mfma_f32_32x32x16_bf16 v[64:79], v[220:223], v[8:11], v[64:79]
	v_pk_mul_f32 v[52:53], v[52:53], v[0:1] op_sel_hi:[1,0]
	v_pk_mul_f32 v[54:55], v[54:55], v[0:1] op_sel_hi:[1,0]
	v_pk_mul_f32 v[56:57], v[56:57], v[0:1] op_sel_hi:[1,0]
	v_pk_mul_f32 v[58:59], v[58:59], v[0:1] op_sel_hi:[1,0]
	v_pk_mul_f32 v[60:61], v[60:61], v[0:1] op_sel_hi:[1,0]
	v_pk_mul_f32 v[62:63], v[62:63], v[0:1] op_sel_hi:[1,0]
	v_pk_mul_f32 v[32:33], v[32:33], v[0:1] op_sel_hi:[1,0]
	v_pk_mul_f32 v[34:35], v[34:35], v[0:1] op_sel_hi:[1,0]
	v_mfma_f32_32x32x16_bf16 v[48:63], v[224:227], v[8:11], v[48:63]
	v_pk_mul_f32 v[36:37], v[36:37], v[0:1] op_sel_hi:[1,0]
	v_pk_mul_f32 v[38:39], v[38:39], v[0:1] op_sel_hi:[1,0]
	v_pk_mul_f32 v[40:41], v[40:41], v[0:1] op_sel_hi:[1,0]
	v_pk_mul_f32 v[42:43], v[42:43], v[0:1] op_sel_hi:[1,0]
	v_pk_mul_f32 v[44:45], v[44:45], v[0:1] op_sel_hi:[1,0]
	v_pk_mul_f32 v[46:47], v[46:47], v[0:1] op_sel_hi:[1,0]
	v_pk_mul_f32 v[16:17], v[16:17], v[0:1] op_sel_hi:[1,0]
	v_pk_mul_f32 v[18:19], v[18:19], v[0:1] op_sel_hi:[1,0]
	v_mfma_f32_32x32x16_bf16 v[32:47], v[228:231], v[8:11], v[32:47]
	v_pk_mul_f32 v[20:21], v[20:21], v[0:1] op_sel_hi:[1,0]
	v_pk_mul_f32 v[22:23], v[22:23], v[0:1] op_sel_hi:[1,0]
	v_pk_mul_f32 v[24:25], v[24:25], v[0:1] op_sel_hi:[1,0]
	v_pk_mul_f32 v[26:27], v[26:27], v[0:1] op_sel_hi:[1,0]
	v_pk_mul_f32 v[28:29], v[28:29], v[0:1] op_sel_hi:[1,0]
	v_pk_mul_f32 v[30:31], v[30:31], v[0:1] op_sel_hi:[1,0]
	v_mov_b32_e32 v128, v215
	v_mov_b32_e32 v133, v4
	v_mfma_f32_32x32x16_bf16 v[16:31], v[198:201], v[8:11], v[16:31]
	s_waitcnt lgkmcnt(0)
	v_mfma_f32_32x32x16_bf16 v[64:79], v[232:235], v[12:15], v[64:79]
	v_mfma_f32_32x32x16_bf16 v[48:63], v[236:239], v[12:15], v[48:63]
	v_mfma_f32_32x32x16_bf16 v[32:47], v[240:243], v[12:15], v[32:47]
	v_mfma_f32_32x32x16_bf16 v[16:31], v[244:247], v[12:15], v[16:31]
	s_or_b32 s0, s24, s56
	s_and_b32 s0, s0, 0xff
	s_cmp_lg_u32 s0, 0
	s_cbranch_scc1 .LBB0_603

.LBB0_623:
	s_waitcnt lgkmcnt(0)
	v_add_f32_e32 v0, v128, v4
	v_rcp_f32_e32 v14, v0
	v_add_u32_e32 v80, v175, v188
	s_ashr_i32 s21, s20, 31
	s_lshl_b32 s0, s17, 7
	v_pk_mul_f32 v[2:3], v[64:65], v[14:15] op_sel_hi:[1,0]
	v_pk_mul_f32 v[4:5], v[66:67], v[14:15] op_sel_hi:[1,0]
	v_cvt_pk_bf16_f32 v2, v2, v3
	v_cvt_pk_bf16_f32 v3, v4, v5
	v_pk_mul_f32 v[4:5], v[68:69], v[14:15] op_sel_hi:[1,0]
	v_pk_mul_f32 v[6:7], v[70:71], v[14:15] op_sel_hi:[1,0]
	v_cvt_pk_bf16_f32 v4, v4, v5
	v_cvt_pk_bf16_f32 v5, v6, v7
	ds_write2_b64 v80, v[2:3], v[4:5] offset1:2
	v_pk_mul_f32 v[2:3], v[72:73], v[14:15] op_sel_hi:[1,0]
	v_pk_mul_f32 v[4:5], v[74:75], v[14:15] op_sel_hi:[1,0]
	s_lshl_b64 s[10:11], s[20:21], 11
	v_readlane_b32 s1, v254, 3
	v_cvt_pk_bf16_f32 v2, v2, v3
	v_cvt_pk_bf16_f32 v3, v4, v5
	v_pk_mul_f32 v[4:5], v[76:77], v[14:15] op_sel_hi:[1,0]
	v_pk_mul_f32 v[6:7], v[78:79], v[14:15] op_sel_hi:[1,0]
	s_add_u32 s1, s10, s1
	v_cvt_pk_bf16_f32 v4, v4, v5
	v_cvt_pk_bf16_f32 v5, v6, v7
	s_addc_u32 s11, s11, 0
	s_lshl_b32 s10, s16, 6
	ds_write2_b64 v80, v[2:3], v[4:5] offset0:4 offset1:6
	v_pk_mul_f32 v[2:3], v[48:49], v[14:15] op_sel_hi:[1,0]
	v_pk_mul_f32 v[4:5], v[50:51], v[14:15] op_sel_hi:[1,0]
	s_add_u32 s10, s1, s10
	v_cvt_pk_bf16_f32 v2, v2, v3
	v_cvt_pk_bf16_f32 v3, v4, v5
	v_pk_mul_f32 v[4:5], v[52:53], v[14:15] op_sel_hi:[1,0]
	v_pk_mul_f32 v[6:7], v[54:55], v[14:15] op_sel_hi:[1,0]
	s_addc_u32 s11, s11, 0
	s_ashr_i32 s1, s0, 31
	v_cvt_pk_bf16_f32 v4, v4, v5
	v_cvt_pk_bf16_f32 v5, v6, v7
	ds_write2_b64 v80, v[2:3], v[4:5] offset0:8 offset1:10
	v_pk_mul_f32 v[2:3], v[56:57], v[14:15] op_sel_hi:[1,0]
	v_pk_mul_f32 v[4:5], v[58:59], v[14:15] op_sel_hi:[1,0]
	s_lshl_b64 s[12:13], s[0:1], 1
	v_cvt_pk_bf16_f32 v2, v2, v3
	v_cvt_pk_bf16_f32 v3, v4, v5
	v_pk_mul_f32 v[4:5], v[60:61], v[14:15] op_sel_hi:[1,0]
	v_pk_mul_f32 v[6:7], v[62:63], v[14:15] op_sel_hi:[1,0]
	s_add_u32 s0, s96, s12
	v_cvt_pk_bf16_f32 v4, v4, v5
	v_cvt_pk_bf16_f32 v5, v6, v7
	s_addc_u32 s1, s97, s13
	ds_write2_b64 v80, v[2:3], v[4:5] offset0:12 offset1:14
	v_or_b32_e32 v68, s10, v164
	v_mov_b64_e32 v[2:3], s[0:1]
	v_mad_u64_u32 v[4:5], s[0:1], v68, s43, v[2:3]
	v_mad_i32_i24 v5, s11, v211, v5
	s_mov_b64 s[14:15], 0x1200
	v_lshl_add_u64 v[56:57], v[4:5], 0, s[14:15]
	v_lshlrev_b32_e32 v0, 1, v166
	s_waitcnt lgkmcnt(0)
	v_lshl_add_u64 v[4:5], v[56:57], 0, v[0:1]
	flat_load_dwordx4 v[48:51], v[4:5]
	v_or_b32_e32 v66, s10, v168
	v_mad_u64_u32 v[4:5], s[0:1], v66, s43, v[2:3]
	v_mad_i32_i24 v5, s11, v211, v5
	v_lshl_add_u64 v[58:59], v[4:5], 0, s[14:15]
	v_lshl_add_u64 v[4:5], v[58:59], 0, v[0:1]
	flat_load_dwordx4 v[10:13], v[4:5]
	v_add_u32_e32 v15, v185, v186
	ds_read_b128 v[52:55], v15
	v_lshl_add_u64 v[64:65], s[10:11], 0, v[176:177]
	v_mad_u64_u32 v[4:5], s[0:1], v64, s43, v[2:3]
	v_mad_i32_i24 v5, v65, s43, v5
	s_waitcnt lgkmcnt(0)
	v_lshlrev_b32_e32 v70, 16, v52
	v_and_b32_e32 v71, 0xffff0000, v52
	v_lshl_add_u64 v[60:61], v[4:5], 0, s[14:15]
	v_lshl_add_u64 v[4:5], v[60:61], 0, v[0:1]
	flat_load_dwordx4 v[6:9], v[4:5]
	v_lshlrev_b32_e32 v52, 16, v53
	v_and_b32_e32 v53, 0xffff0000, v53
	v_mov_b32_e32 v69, s11
	v_lshl_add_u64 v[4:5], s[10:11], 0, v[178:179]
	v_mad_u64_u32 v[2:3], s[0:1], v4, s43, v[2:3]
	v_mad_i32_i24 v3, v5, s43, v3
	v_lshl_add_u64 v[62:63], v[2:3], 0, s[14:15]
	v_lshl_add_u64 v[2:3], v[62:63], 0, v[0:1]
	flat_load_dwordx4 v[2:5], v[2:3]
	v_lshlrev_b32_e32 v232, 1, v174
	v_mov_b32_e32 v233, 0
	v_lshl_add_u64 v[234:235], v[56:57], 0, v[232:233]
	global_load_dwordx4 v[216:219], v[234:235], off
	v_lshl_add_u64 v[234:235], v[58:59], 0, v[232:233]
	global_load_dwordx4 v[220:223], v[234:235], off
	v_lshl_add_u64 v[234:235], v[60:61], 0, v[232:233]
	global_load_dwordx4 v[224:227], v[234:235], off
	v_lshl_add_u64 v[234:235], v[62:63], 0, v[232:233]
	global_load_dwordx4 v[228:231], v[234:235], off
	v_mov_b32_e32 v67, s11
	s_waitcnt vmcnt(0)
	v_mov_b32_e32 v147, v99
	v_mov_b32_e32 v146, v98
	v_mov_b32_e32 v145, v97
	v_mov_b32_e32 v144, v96
	v_mov_b32_e32 v143, v103
	v_mov_b32_e32 v142, v102
	v_mov_b32_e32 v141, v101
	v_mov_b32_e32 v140, v100
	v_mov_b32_e32 v139, v107
	v_mov_b32_e32 v138, v106
	v_mov_b32_e32 v137, v105
	v_mov_b32_e32 v136, v104
	v_mov_b32_e32 v135, v111
	v_mov_b32_e32 v134, v110
	v_mov_b32_e32 v133, v109
	v_mov_b32_e32 v132, v108
	v_mov_b32_e32 v131, v115
	v_mov_b32_e32 v130, v114
	v_mov_b32_e32 v129, v113
	v_mov_b32_e32 v128, v112
	v_mov_b32_e32 v93, v119
	v_mov_b32_e32 v92, v118
	v_mov_b32_e32 v91, v117
	v_mov_b32_e32 v90, v116
	v_mov_b32_e32 v89, v123
	v_mov_b32_e32 v88, v122
	v_mov_b32_e32 v87, v121
	v_mov_b32_e32 v86, v120
	v_mov_b32_e32 v85, v127
	v_mov_b32_e32 v84, v126
	v_mov_b32_e32 v83, v125
	v_mov_b32_e32 v82, v124
	s_mov_b32 s59, s64
	s_mov_b32 s63, s55
	s_mov_b32 s19, s54
	s_mov_b32 s71, s60
	s_mov_b32 s53, s70
	s_mov_b32 s65, s57
	s_mov_b32 s69, s52
	s_mov_b32 s67, s51
	s_mov_b32 s50, s68
	s_mov_b32 s98, s61
	v_mov_b32_e32 v183, v171
	s_mov_b32 s21, s56
	v_mov_b32_e32 v94, v182
	s_mov_b64 s[26:27], s[4:5]
	v_lshlrev_b32_e32 v72, 16, v48
	v_and_b32_e32 v73, 0xffff0000, v48
	v_mul_f32_e32 v48, 0xbfb8aa3b, v72
	v_exp_f32_e32 v48, v48
	s_nop 0
	v_add_f32_e32 v48, 1.0, v48
	v_rcp_f32_e32 v74, v48
	v_mul_f32_e32 v48, 0xbfb8aa3b, v73
	v_exp_f32_e32 v48, v48
	s_nop 0
	v_add_f32_e32 v48, 1.0, v48
	v_rcp_f32_e32 v75, v48
	v_lshlrev_b32_e32 v48, 16, v49
	v_and_b32_e32 v49, 0xffff0000, v49
	v_pk_mul_f32 v[72:73], v[74:75], v[72:73]
	s_nop 0
	v_pk_mul_f32 v[70:71], v[72:73], v[70:71]
	v_mul_f32_e32 v72, 0xbfb8aa3b, v48
	v_mul_f32_e32 v73, 0xbfb8aa3b, v49
	v_exp_f32_e32 v72, v72
	v_exp_f32_e32 v73, v73
	v_add_f32_e32 v72, 1.0, v72
	v_add_f32_e32 v73, 1.0, v73
	v_rcp_f32_e32 v72, v72
	v_rcp_f32_e32 v73, v73
	s_nop 0
	v_pk_mul_f32 v[48:49], v[72:73], v[48:49]
	v_lshlrev_b32_e32 v72, 16, v50
	v_and_b32_e32 v73, 0xffff0000, v50
	v_mul_f32_e32 v50, 0xbfb8aa3b, v72
	v_exp_f32_e32 v50, v50
	v_pk_mul_f32 v[48:49], v[48:49], v[52:53]
	v_lshlrev_b32_e32 v52, 16, v54
	v_and_b32_e32 v53, 0xffff0000, v54
	v_add_f32_e32 v50, 1.0, v50
	v_rcp_f32_e32 v74, v50
	v_mul_f32_e32 v50, 0xbfb8aa3b, v73
	v_exp_f32_e32 v50, v50
	s_nop 0
	v_add_f32_e32 v50, 1.0, v50
	v_rcp_f32_e32 v75, v50
	v_lshlrev_b32_e32 v50, 16, v51
	v_and_b32_e32 v51, 0xffff0000, v51
	v_mul_f32_e32 v54, 0xbfb8aa3b, v50
	v_pk_mul_f32 v[72:73], v[74:75], v[72:73]
	v_exp_f32_e32 v54, v54
	v_pk_mul_f32 v[72:73], v[72:73], v[52:53]
	v_lshlrev_b32_e32 v52, 16, v55
	v_and_b32_e32 v53, 0xffff0000, v55
	v_mul_f32_e32 v55, 0xbfb8aa3b, v51
	v_exp_f32_e32 v55, v55
	v_add_f32_e32 v54, 1.0, v54
	v_rcp_f32_e32 v54, v54
	v_add_f32_e32 v55, 1.0, v55
	v_rcp_f32_e32 v55, v55
	s_nop 0
	v_pk_mul_f32 v[50:51], v[54:55], v[50:51]
	s_nop 0
	v_pk_mul_f32 v[50:51], v[50:51], v[52:53]
	v_cvt_pk_bf16_f32 v53, v48, v49
	v_lshlrev_b64 v[48:49], 12, v[68:69]
	v_lshlrev_b32_e32 v68, 16, v10
	v_and_b32_e32 v69, 0xffff0000, v10
	v_mul_f32_e32 v10, 0xbfb8aa3b, v68
	v_exp_f32_e32 v10, v10
	v_cvt_pk_bf16_f32 v52, v70, v71
	v_lshl_add_u64 v[48:49], s[90:91], 0, v[48:49]
	v_lshl_add_u64 v[48:49], v[48:49], 0, s[12:13]
	v_add_f32_e32 v10, 1.0, v10
	v_rcp_f32_e32 v70, v10
	v_mul_f32_e32 v10, 0xbfb8aa3b, v69
	v_exp_f32_e32 v10, v10
	v_cvt_pk_bf16_f32 v54, v72, v73
	v_cvt_pk_bf16_f32 v55, v50, v51
	v_lshl_add_u64 v[50:51], v[48:49], 0, v[0:1]
	flat_store_dwordx4 v[50:51], v[52:55]
	ds_read_b128 v[52:55], v15 offset:1152
	v_add_f32_e32 v10, 1.0, v10
	v_rcp_f32_e32 v71, v10
	v_lshlrev_b32_e32 v10, 16, v11
	v_and_b32_e32 v11, 0xffff0000, v11
	s_waitcnt lgkmcnt(0)
	v_lshlrev_b32_e32 v48, 16, v52
	v_and_b32_e32 v49, 0xffff0000, v52
	v_pk_mul_f32 v[68:69], v[70:71], v[68:69]
	v_lshlrev_b32_e32 v52, 16, v53
	v_pk_mul_f32 v[48:49], v[68:69], v[48:49]
	v_mul_f32_e32 v68, 0xbfb8aa3b, v10
	v_mul_f32_e32 v69, 0xbfb8aa3b, v11
	v_exp_f32_e32 v68, v68
	v_exp_f32_e32 v69, v69
	v_and_b32_e32 v53, 0xffff0000, v53
	v_add_f32_e32 v68, 1.0, v68
	v_add_f32_e32 v69, 1.0, v69
	v_rcp_f32_e32 v68, v68
	v_rcp_f32_e32 v69, v69
	s_nop 0
	v_pk_mul_f32 v[10:11], v[68:69], v[10:11]
	v_lshlrev_b32_e32 v68, 16, v12
	v_and_b32_e32 v69, 0xffff0000, v12
	v_mul_f32_e32 v12, 0xbfb8aa3b, v68
	v_exp_f32_e32 v12, v12
	v_pk_mul_f32 v[52:53], v[10:11], v[52:53]
	v_lshlrev_b32_e32 v10, 16, v54
	v_and_b32_e32 v11, 0xffff0000, v54
	v_add_f32_e32 v12, 1.0, v12
	v_rcp_f32_e32 v70, v12
	v_mul_f32_e32 v12, 0xbfb8aa3b, v69
	v_exp_f32_e32 v12, v12
	s_nop 0
	v_add_f32_e32 v12, 1.0, v12
	v_rcp_f32_e32 v71, v12
	v_lshlrev_b32_e32 v12, 16, v13
	v_and_b32_e32 v13, 0xffff0000, v13
	v_mul_f32_e32 v54, 0xbfb8aa3b, v12
	v_pk_mul_f32 v[68:69], v[70:71], v[68:69]
	v_exp_f32_e32 v54, v54
	v_pk_mul_f32 v[68:69], v[68:69], v[10:11]
	v_lshlrev_b32_e32 v10, 16, v55
	v_and_b32_e32 v11, 0xffff0000, v55
	v_mul_f32_e32 v55, 0xbfb8aa3b, v13
	v_exp_f32_e32 v55, v55
	v_add_f32_e32 v54, 1.0, v54
	v_rcp_f32_e32 v54, v54
	v_add_f32_e32 v55, 1.0, v55
	v_rcp_f32_e32 v55, v55
	s_nop 0
	v_pk_mul_f32 v[12:13], v[54:55], v[12:13]
	s_nop 0
	v_pk_mul_f32 v[54:55], v[12:13], v[10:11]
	v_cvt_pk_bf16_f32 v10, v48, v49
	v_cvt_pk_bf16_f32 v13, v54, v55
	v_lshlrev_b32_e32 v54, 16, v6
	v_and_b32_e32 v55, 0xffff0000, v6
	v_mul_f32_e32 v6, 0xbfb8aa3b, v54
	v_exp_f32_e32 v6, v6
	v_lshlrev_b64 v[48:49], 12, v[66:67]
	v_lshl_add_u64 v[48:49], s[90:91], 0, v[48:49]
	v_lshl_add_u64 v[48:49], v[48:49], 0, s[12:13]
	v_add_f32_e32 v6, 1.0, v6
	v_rcp_f32_e32 v66, v6
	v_mul_f32_e32 v6, 0xbfb8aa3b, v55
	v_exp_f32_e32 v6, v6
	v_cvt_pk_bf16_f32 v11, v52, v53
	v_cvt_pk_bf16_f32 v12, v68, v69
	v_lshl_add_u64 v[52:53], v[48:49], 0, v[0:1]
	flat_store_dwordx4 v[52:53], v[10:13]
	ds_read_b128 v[10:13], v15 offset:2304
	v_add_f32_e32 v6, 1.0, v6
	v_rcp_f32_e32 v67, v6
	v_lshlrev_b32_e32 v6, 16, v7
	v_and_b32_e32 v7, 0xffff0000, v7
	s_waitcnt lgkmcnt(0)
	v_lshlrev_b32_e32 v48, 16, v10
	v_and_b32_e32 v49, 0xffff0000, v10
	v_pk_mul_f32 v[54:55], v[66:67], v[54:55]
	v_lshlrev_b32_e32 v10, 16, v11
	v_pk_mul_f32 v[48:49], v[54:55], v[48:49]
	v_mul_f32_e32 v54, 0xbfb8aa3b, v6
	v_mul_f32_e32 v55, 0xbfb8aa3b, v7
	v_exp_f32_e32 v54, v54
	v_exp_f32_e32 v55, v55
	v_and_b32_e32 v11, 0xffff0000, v11
	v_add_f32_e32 v54, 1.0, v54
	v_add_f32_e32 v55, 1.0, v55
	v_rcp_f32_e32 v54, v54
	v_rcp_f32_e32 v55, v55
	s_nop 0
	v_pk_mul_f32 v[6:7], v[54:55], v[6:7]
	v_lshlrev_b32_e32 v54, 16, v8
	v_and_b32_e32 v55, 0xffff0000, v8
	v_mul_f32_e32 v8, 0xbfb8aa3b, v54
	v_exp_f32_e32 v8, v8
	v_pk_mul_f32 v[10:11], v[6:7], v[10:11]
	v_lshlrev_b32_e32 v6, 16, v12
	v_and_b32_e32 v7, 0xffff0000, v12
	v_add_f32_e32 v8, 1.0, v8
	v_rcp_f32_e32 v66, v8
	v_mul_f32_e32 v8, 0xbfb8aa3b, v55
	v_exp_f32_e32 v8, v8
	s_nop 0
	v_add_f32_e32 v8, 1.0, v8
	v_rcp_f32_e32 v67, v8
	v_lshlrev_b32_e32 v8, 16, v9
	v_and_b32_e32 v9, 0xffff0000, v9
	v_mul_f32_e32 v12, 0xbfb8aa3b, v8
	v_pk_mul_f32 v[54:55], v[66:67], v[54:55]
	v_exp_f32_e32 v12, v12
	v_pk_mul_f32 v[54:55], v[54:55], v[6:7]
	v_lshlrev_b32_e32 v6, 16, v13
	v_and_b32_e32 v7, 0xffff0000, v13
	v_mul_f32_e32 v13, 0xbfb8aa3b, v9
	v_exp_f32_e32 v13, v13
	v_add_f32_e32 v12, 1.0, v12
	v_rcp_f32_e32 v12, v12
	v_add_f32_e32 v13, 1.0, v13
	v_rcp_f32_e32 v13, v13
	s_nop 0
	v_pk_mul_f32 v[8:9], v[12:13], v[8:9]
	s_nop 0
	v_pk_mul_f32 v[12:13], v[8:9], v[6:7]
	v_cvt_pk_bf16_f32 v6, v48, v49
	v_cvt_pk_bf16_f32 v9, v12, v13
	v_lshlrev_b32_e32 v12, 16, v2
	v_and_b32_e32 v13, 0xffff0000, v2
	v_mul_f32_e32 v2, 0xbfb8aa3b, v12
	v_exp_f32_e32 v2, v2
	v_cvt_pk_bf16_f32 v7, v10, v11
	v_lshlrev_b64 v[10:11], 12, v[64:65]
	v_lshl_add_u64 v[10:11], s[90:91], 0, v[10:11]
	v_add_f32_e32 v2, 1.0, v2
	v_rcp_f32_e32 v48, v2
	v_mul_f32_e32 v2, 0xbfb8aa3b, v13
	v_exp_f32_e32 v2, v2
	v_lshl_add_u64 v[10:11], v[10:11], 0, s[12:13]
	v_cvt_pk_bf16_f32 v8, v54, v55
	v_lshl_add_u64 v[54:55], v[10:11], 0, v[0:1]
	flat_store_dwordx4 v[54:55], v[6:9]
	ds_read_b128 v[6:9], v15 offset:3456
	v_add_f32_e32 v2, 1.0, v2
	v_rcp_f32_e32 v49, v2
	v_lshlrev_b32_e32 v2, 16, v3
	v_and_b32_e32 v3, 0xffff0000, v3
	s_waitcnt lgkmcnt(0)
	v_lshlrev_b32_e32 v10, 16, v6
	v_and_b32_e32 v11, 0xffff0000, v6
	v_pk_mul_f32 v[12:13], v[48:49], v[12:13]
	v_lshlrev_b32_e32 v6, 16, v7
	v_pk_mul_f32 v[10:11], v[12:13], v[10:11]
	v_mul_f32_e32 v12, 0xbfb8aa3b, v2
	v_mul_f32_e32 v13, 0xbfb8aa3b, v3
	v_exp_f32_e32 v12, v12
	v_exp_f32_e32 v13, v13
	v_and_b32_e32 v7, 0xffff0000, v7
	v_add_f32_e32 v12, 1.0, v12
	v_add_f32_e32 v13, 1.0, v13
	v_rcp_f32_e32 v12, v12
	v_rcp_f32_e32 v13, v13
	s_nop 0
	v_pk_mul_f32 v[2:3], v[12:13], v[2:3]
	v_lshlrev_b32_e32 v12, 16, v4
	v_and_b32_e32 v13, 0xffff0000, v4
	v_mul_f32_e32 v4, 0xbfb8aa3b, v12
	v_exp_f32_e32 v4, v4
	v_pk_mul_f32 v[6:7], v[2:3], v[6:7]
	v_lshlrev_b32_e32 v2, 16, v8
	v_and_b32_e32 v3, 0xffff0000, v8
	v_add_f32_e32 v4, 1.0, v4
	v_rcp_f32_e32 v48, v4
	v_mul_f32_e32 v4, 0xbfb8aa3b, v13
	v_exp_f32_e32 v4, v4
	s_nop 0
	v_add_f32_e32 v4, 1.0, v4
	v_rcp_f32_e32 v49, v4
	v_lshlrev_b32_e32 v4, 16, v5
	v_and_b32_e32 v5, 0xffff0000, v5
	v_mul_f32_e32 v8, 0xbfb8aa3b, v4
	v_pk_mul_f32 v[12:13], v[48:49], v[12:13]
	v_exp_f32_e32 v8, v8
	v_pk_mul_f32 v[12:13], v[12:13], v[2:3]
	v_lshlrev_b32_e32 v2, 16, v9
	v_and_b32_e32 v3, 0xffff0000, v9
	v_mul_f32_e32 v9, 0xbfb8aa3b, v5
	v_exp_f32_e32 v9, v9
	v_add_f32_e32 v8, 1.0, v8
	v_rcp_f32_e32 v8, v8
	v_lshl_add_u64 v[48:49], s[10:11], 0, v[180:181]
	v_add_f32_e32 v9, 1.0, v9
	v_rcp_f32_e32 v9, v9
	s_nop 0
	v_pk_mul_f32 v[4:5], v[8:9], v[4:5]
	s_nop 0
	v_pk_mul_f32 v[8:9], v[4:5], v[2:3]
	v_cvt_pk_bf16_f32 v3, v6, v7
	v_lshlrev_b64 v[6:7], 12, v[48:49]
	v_lshl_add_u64 v[6:7], s[90:91], 0, v[6:7]
	v_lshl_add_u64 v[48:49], v[6:7], 0, s[12:13]
	v_cvt_pk_bf16_f32 v2, v10, v11
	v_cvt_pk_bf16_f32 v4, v12, v13
	v_cvt_pk_bf16_f32 v5, v8, v9
	v_lshl_add_u64 v[6:7], v[48:49], 0, v[0:1]
	flat_store_dwordx4 v[6:7], v[2:5]
	v_pk_mul_f32 v[6:7], v[38:39], v[14:15] op_sel_hi:[1,0]
	v_lshlrev_b32_e32 v0, 1, v174
	v_pk_mul_f32 v[2:3], v[32:33], v[14:15] op_sel_hi:[1,0]
	v_pk_mul_f32 v[4:5], v[34:35], v[14:15] op_sel_hi:[1,0]
	v_cvt_pk_bf16_f32 v2, v2, v3
	v_cvt_pk_bf16_f32 v3, v4, v5
	v_pk_mul_f32 v[4:5], v[36:37], v[14:15] op_sel_hi:[1,0]
	s_mov_b64 s[12:13], s[86:87]
	v_cvt_pk_bf16_f32 v4, v4, v5
	v_cvt_pk_bf16_f32 v5, v6, v7
	ds_write2_b64 v80, v[2:3], v[4:5] offset1:2
	v_pk_mul_f32 v[2:3], v[40:41], v[14:15] op_sel_hi:[1,0]
	v_pk_mul_f32 v[4:5], v[42:43], v[14:15] op_sel_hi:[1,0]
	v_cvt_pk_bf16_f32 v2, v2, v3
	v_cvt_pk_bf16_f32 v3, v4, v5
	v_pk_mul_f32 v[4:5], v[44:45], v[14:15] op_sel_hi:[1,0]
	v_pk_mul_f32 v[6:7], v[46:47], v[14:15] op_sel_hi:[1,0]
	v_cvt_pk_bf16_f32 v4, v4, v5
	v_cvt_pk_bf16_f32 v5, v6, v7
	ds_write2_b64 v80, v[2:3], v[4:5] offset0:4 offset1:6
	v_pk_mul_f32 v[2:3], v[16:17], v[14:15] op_sel_hi:[1,0]
	v_pk_mul_f32 v[4:5], v[18:19], v[14:15] op_sel_hi:[1,0]
	v_cvt_pk_bf16_f32 v2, v2, v3
	v_cvt_pk_bf16_f32 v3, v4, v5
	v_pk_mul_f32 v[4:5], v[20:21], v[14:15] op_sel_hi:[1,0]
	v_pk_mul_f32 v[6:7], v[22:23], v[14:15] op_sel_hi:[1,0]
	v_cvt_pk_bf16_f32 v4, v4, v5
	v_cvt_pk_bf16_f32 v5, v6, v7
	ds_write2_b64 v80, v[2:3], v[4:5] offset0:8 offset1:10
	v_pk_mul_f32 v[2:3], v[24:25], v[14:15] op_sel_hi:[1,0]
	v_pk_mul_f32 v[4:5], v[26:27], v[14:15] op_sel_hi:[1,0]
	v_cvt_pk_bf16_f32 v2, v2, v3
	v_cvt_pk_bf16_f32 v3, v4, v5
	v_pk_mul_f32 v[4:5], v[28:29], v[14:15] op_sel_hi:[1,0]
	v_pk_mul_f32 v[6:7], v[30:31], v[14:15] op_sel_hi:[1,0]
	v_cvt_pk_bf16_f32 v4, v4, v5
	v_cvt_pk_bf16_f32 v5, v6, v7
	ds_write2_b64 v80, v[2:3], v[4:5] offset0:12 offset1:14
	s_waitcnt lgkmcnt(0)
	v_lshl_add_u64 v[2:3], v[56:57], 0, v[0:1]
	v_mov_b32_e32 v16, v216
	v_mov_b32_e32 v17, v217
	v_mov_b32_e32 v18, v218
	v_mov_b32_e32 v19, v219
	v_lshl_add_u64 v[2:3], v[58:59], 0, v[0:1]
	v_mov_b32_e32 v10, v220
	v_mov_b32_e32 v11, v221
	v_mov_b32_e32 v12, v222
	v_mov_b32_e32 v13, v223
	v_lshl_add_u64 v[2:3], v[60:61], 0, v[0:1]
	v_mov_b32_e32 v6, v224
	v_mov_b32_e32 v7, v225
	v_mov_b32_e32 v8, v226
	v_mov_b32_e32 v9, v227
	v_lshl_add_u64 v[2:3], v[62:63], 0, v[0:1]
	ds_read_b128 v[20:23], v15
	v_mov_b32_e32 v2, v228
	v_mov_b32_e32 v3, v229
	v_mov_b32_e32 v4, v230
	v_mov_b32_e32 v5, v231
	s_waitcnt lgkmcnt(0)
	v_lshlrev_b32_e32 v24, 16, v20
	v_and_b32_e32 v25, 0xffff0000, v20
	v_lshlrev_b32_e32 v20, 16, v21
	v_and_b32_e32 v21, 0xffff0000, v21
	s_waitcnt vmcnt(4)
	v_lshlrev_b32_e32 v26, 16, v16
	v_mul_f32_e32 v0, 0xbfb8aa3b, v26
	v_exp_f32_e32 v0, v0
	v_and_b32_e32 v27, 0xffff0000, v16
	v_lshlrev_b32_e32 v16, 16, v17
	v_and_b32_e32 v17, 0xffff0000, v17
	v_add_f32_e32 v0, 1.0, v0
	v_rcp_f32_e32 v28, v0
	v_mul_f32_e32 v0, 0xbfb8aa3b, v27
	v_exp_f32_e32 v0, v0
	s_nop 0
	v_add_f32_e32 v0, 1.0, v0
	v_rcp_f32_e32 v29, v0
	v_mul_f32_e32 v0, 0xbfb8aa3b, v16
	v_exp_f32_e32 v0, v0
	v_pk_mul_f32 v[26:27], v[28:29], v[26:27]
	s_nop 0
	v_pk_mul_f32 v[24:25], v[26:27], v[24:25]
	v_add_f32_e32 v0, 1.0, v0
	v_rcp_f32_e32 v26, v0
	v_mul_f32_e32 v0, 0xbfb8aa3b, v17
	v_exp_f32_e32 v0, v0
	s_nop 0
	v_add_f32_e32 v0, 1.0, v0
	v_rcp_f32_e32 v27, v0
	s_nop 0
	v_pk_mul_f32 v[16:17], v[26:27], v[16:17]
	v_lshlrev_b32_e32 v26, 16, v18
	v_mul_f32_e32 v0, 0xbfb8aa3b, v26
	v_exp_f32_e32 v0, v0
	v_and_b32_e32 v27, 0xffff0000, v18
	v_lshlrev_b32_e32 v18, 16, v19
	v_and_b32_e32 v19, 0xffff0000, v19
	v_add_f32_e32 v0, 1.0, v0
	v_rcp_f32_e32 v28, v0
	v_mul_f32_e32 v0, 0xbfb8aa3b, v27
	v_exp_f32_e32 v0, v0
	v_pk_mul_f32 v[20:21], v[16:17], v[20:21]
	v_lshlrev_b32_e32 v16, 16, v22
	v_and_b32_e32 v17, 0xffff0000, v22
	v_add_f32_e32 v0, 1.0, v0
	v_rcp_f32_e32 v29, v0
	v_mul_f32_e32 v0, 0xbfb8aa3b, v18
	v_exp_f32_e32 v0, v0
	v_pk_mul_f32 v[26:27], v[28:29], v[26:27]
	s_nop 0
	v_pk_mul_f32 v[26:27], v[26:27], v[16:17]
	v_add_f32_e32 v0, 1.0, v0
	v_rcp_f32_e32 v22, v0
	v_mul_f32_e32 v0, 0xbfb8aa3b, v19
	v_exp_f32_e32 v0, v0
	v_lshlrev_b32_e32 v16, 16, v23
	v_and_b32_e32 v17, 0xffff0000, v23
	v_add_f32_e32 v0, 1.0, v0
	v_rcp_f32_e32 v23, v0
	s_nop 0
	v_pk_mul_f32 v[18:19], v[22:23], v[18:19]
	s_nop 0
	v_pk_mul_f32 v[22:23], v[18:19], v[16:17]
	v_cvt_pk_bf16_f32 v16, v24, v25
	v_cvt_pk_bf16_f32 v19, v22, v23
	v_lshlrev_b32_e32 v22, 16, v10
	v_mul_f32_e32 v0, 0xbfb8aa3b, v22
	v_exp_f32_e32 v0, v0
	v_and_b32_e32 v23, 0xffff0000, v10
	v_cvt_pk_bf16_f32 v17, v20, v21
	v_cvt_pk_bf16_f32 v18, v26, v27
	v_add_f32_e32 v0, 1.0, v0
	v_rcp_f32_e32 v24, v0
	v_mul_f32_e32 v0, 0xbfb8aa3b, v23
	v_exp_f32_e32 v0, v0
	flat_store_dwordx4 v[50:51], v[16:19] offset:128
	v_lshlrev_b32_e32 v10, 16, v11
	ds_read_b128 v[16:19], v15 offset:1152
	v_add_f32_e32 v0, 1.0, v0
	v_rcp_f32_e32 v25, v0
	v_mul_f32_e32 v0, 0xbfb8aa3b, v10
	v_exp_f32_e32 v0, v0
	s_waitcnt lgkmcnt(0)
	v_lshlrev_b32_e32 v20, 16, v16
	v_and_b32_e32 v21, 0xffff0000, v16
	v_pk_mul_f32 v[22:23], v[24:25], v[22:23]
	v_and_b32_e32 v11, 0xffff0000, v11
	v_add_f32_e32 v0, 1.0, v0
	v_pk_mul_f32 v[20:21], v[22:23], v[20:21]
	v_rcp_f32_e32 v22, v0
	v_mul_f32_e32 v0, 0xbfb8aa3b, v11
	v_exp_f32_e32 v0, v0
	v_lshlrev_b32_e32 v16, 16, v17
	v_and_b32_e32 v17, 0xffff0000, v17
	v_add_f32_e32 v0, 1.0, v0
	v_rcp_f32_e32 v23, v0
	s_nop 0
	v_pk_mul_f32 v[10:11], v[22:23], v[10:11]
	v_lshlrev_b32_e32 v22, 16, v12
	v_mul_f32_e32 v0, 0xbfb8aa3b, v22
	v_exp_f32_e32 v0, v0
	v_and_b32_e32 v23, 0xffff0000, v12
	v_lshlrev_b32_e32 v12, 16, v13
	v_and_b32_e32 v13, 0xffff0000, v13
	v_add_f32_e32 v0, 1.0, v0
	v_rcp_f32_e32 v24, v0
	v_mul_f32_e32 v0, 0xbfb8aa3b, v23
	v_exp_f32_e32 v0, v0
	v_pk_mul_f32 v[16:17], v[10:11], v[16:17]
	v_lshlrev_b32_e32 v10, 16, v18
	v_and_b32_e32 v11, 0xffff0000, v18
	v_add_f32_e32 v0, 1.0, v0
	v_rcp_f32_e32 v25, v0
	v_mul_f32_e32 v0, 0xbfb8aa3b, v12
	v_exp_f32_e32 v0, v0
	v_pk_mul_f32 v[22:23], v[24:25], v[22:23]
	s_nop 0
	v_pk_mul_f32 v[22:23], v[22:23], v[10:11]
	v_add_f32_e32 v0, 1.0, v0
	v_rcp_f32_e32 v18, v0
	v_mul_f32_e32 v0, 0xbfb8aa3b, v13
	v_exp_f32_e32 v0, v0
	v_lshlrev_b32_e32 v10, 16, v19
	v_and_b32_e32 v11, 0xffff0000, v19
	v_add_f32_e32 v0, 1.0, v0
	v_rcp_f32_e32 v19, v0
	s_nop 0
	v_pk_mul_f32 v[12:13], v[18:19], v[12:13]
	s_nop 0
	v_pk_mul_f32 v[18:19], v[12:13], v[10:11]
	v_cvt_pk_bf16_f32 v10, v20, v21
	v_cvt_pk_bf16_f32 v13, v18, v19
	v_lshlrev_b32_e32 v18, 16, v6
	v_mul_f32_e32 v0, 0xbfb8aa3b, v18
	v_exp_f32_e32 v0, v0
	v_and_b32_e32 v19, 0xffff0000, v6
	v_cvt_pk_bf16_f32 v11, v16, v17
	v_cvt_pk_bf16_f32 v12, v22, v23
	v_add_f32_e32 v0, 1.0, v0
	v_rcp_f32_e32 v20, v0
	v_mul_f32_e32 v0, 0xbfb8aa3b, v19
	v_exp_f32_e32 v0, v0
	flat_store_dwordx4 v[52:53], v[10:13] offset:128
	v_lshlrev_b32_e32 v6, 16, v7
	ds_read_b128 v[10:13], v15 offset:2304
	v_add_f32_e32 v0, 1.0, v0
	v_rcp_f32_e32 v21, v0
	v_mul_f32_e32 v0, 0xbfb8aa3b, v6
	v_exp_f32_e32 v0, v0
	s_waitcnt lgkmcnt(0)
	v_lshlrev_b32_e32 v16, 16, v10
	v_and_b32_e32 v17, 0xffff0000, v10
	v_pk_mul_f32 v[18:19], v[20:21], v[18:19]
	v_and_b32_e32 v7, 0xffff0000, v7
	v_add_f32_e32 v0, 1.0, v0
	v_pk_mul_f32 v[16:17], v[18:19], v[16:17]
	v_rcp_f32_e32 v18, v0
	v_mul_f32_e32 v0, 0xbfb8aa3b, v7
	v_exp_f32_e32 v0, v0
	v_lshlrev_b32_e32 v10, 16, v11
	v_and_b32_e32 v11, 0xffff0000, v11
	v_add_f32_e32 v0, 1.0, v0
	v_rcp_f32_e32 v19, v0
	s_nop 0
	v_pk_mul_f32 v[6:7], v[18:19], v[6:7]
	v_lshlrev_b32_e32 v18, 16, v8
	v_mul_f32_e32 v0, 0xbfb8aa3b, v18
	v_exp_f32_e32 v0, v0
	v_and_b32_e32 v19, 0xffff0000, v8
	v_lshlrev_b32_e32 v8, 16, v9
	v_and_b32_e32 v9, 0xffff0000, v9
	v_add_f32_e32 v0, 1.0, v0
	v_rcp_f32_e32 v20, v0
	v_mul_f32_e32 v0, 0xbfb8aa3b, v19
	v_exp_f32_e32 v0, v0
	v_pk_mul_f32 v[10:11], v[6:7], v[10:11]
	v_lshlrev_b32_e32 v6, 16, v12
	v_and_b32_e32 v7, 0xffff0000, v12
	v_add_f32_e32 v0, 1.0, v0
	v_rcp_f32_e32 v21, v0
	v_mul_f32_e32 v0, 0xbfb8aa3b, v8
	v_exp_f32_e32 v0, v0
	v_pk_mul_f32 v[18:19], v[20:21], v[18:19]
	s_nop 0
	v_pk_mul_f32 v[18:19], v[18:19], v[6:7]
	v_add_f32_e32 v0, 1.0, v0
	v_rcp_f32_e32 v12, v0
	v_mul_f32_e32 v0, 0xbfb8aa3b, v9
	v_exp_f32_e32 v0, v0
	v_lshlrev_b32_e32 v6, 16, v13
	v_and_b32_e32 v7, 0xffff0000, v13
	v_add_f32_e32 v0, 1.0, v0
	v_rcp_f32_e32 v13, v0
	s_nop 0
	v_pk_mul_f32 v[8:9], v[12:13], v[8:9]
	s_nop 0
	v_pk_mul_f32 v[12:13], v[8:9], v[6:7]
	v_cvt_pk_bf16_f32 v6, v16, v17
	v_cvt_pk_bf16_f32 v9, v12, v13
	v_lshlrev_b32_e32 v12, 16, v2
	v_mul_f32_e32 v0, 0xbfb8aa3b, v12
	v_exp_f32_e32 v0, v0
	v_and_b32_e32 v13, 0xffff0000, v2
	v_cvt_pk_bf16_f32 v7, v10, v11
	v_cvt_pk_bf16_f32 v8, v18, v19
	v_add_f32_e32 v0, 1.0, v0
	v_rcp_f32_e32 v14, v0
	v_mul_f32_e32 v0, 0xbfb8aa3b, v13
	v_exp_f32_e32 v0, v0
	flat_store_dwordx4 v[54:55], v[6:9] offset:128
	v_lshlrev_b32_e32 v2, 16, v3
	ds_read_b128 v[6:9], v15 offset:3456
	v_add_f32_e32 v0, 1.0, v0
	v_rcp_f32_e32 v15, v0
	v_mul_f32_e32 v0, 0xbfb8aa3b, v2
	v_exp_f32_e32 v0, v0
	s_waitcnt lgkmcnt(0)
	v_lshlrev_b32_e32 v10, 16, v6
	v_and_b32_e32 v11, 0xffff0000, v6
	v_pk_mul_f32 v[12:13], v[14:15], v[12:13]
	v_and_b32_e32 v3, 0xffff0000, v3
	v_add_f32_e32 v0, 1.0, v0
	v_pk_mul_f32 v[10:11], v[12:13], v[10:11]
	v_rcp_f32_e32 v12, v0
	v_mul_f32_e32 v0, 0xbfb8aa3b, v3
	v_exp_f32_e32 v0, v0
	v_lshlrev_b32_e32 v6, 16, v7
	v_and_b32_e32 v7, 0xffff0000, v7
	v_add_f32_e32 v0, 1.0, v0
	v_rcp_f32_e32 v13, v0
	s_nop 0
	v_pk_mul_f32 v[2:3], v[12:13], v[2:3]
	v_lshlrev_b32_e32 v12, 16, v4
	v_mul_f32_e32 v0, 0xbfb8aa3b, v12
	v_exp_f32_e32 v0, v0
	v_and_b32_e32 v13, 0xffff0000, v4
	v_lshlrev_b32_e32 v4, 16, v5
	v_and_b32_e32 v5, 0xffff0000, v5
	v_add_f32_e32 v0, 1.0, v0
	v_rcp_f32_e32 v14, v0
	v_mul_f32_e32 v0, 0xbfb8aa3b, v13
	v_exp_f32_e32 v0, v0
	v_pk_mul_f32 v[6:7], v[2:3], v[6:7]
	v_lshlrev_b32_e32 v2, 16, v8
	v_and_b32_e32 v3, 0xffff0000, v8
	v_add_f32_e32 v0, 1.0, v0
	v_rcp_f32_e32 v15, v0
	v_mul_f32_e32 v0, 0xbfb8aa3b, v4
	v_exp_f32_e32 v0, v0
	v_pk_mul_f32 v[12:13], v[14:15], v[12:13]
	s_nop 0
	v_pk_mul_f32 v[12:13], v[12:13], v[2:3]
	v_add_f32_e32 v0, 1.0, v0
	v_rcp_f32_e32 v8, v0
	v_mul_f32_e32 v0, 0xbfb8aa3b, v5
	v_exp_f32_e32 v0, v0
	v_lshlrev_b32_e32 v2, 16, v9
	v_and_b32_e32 v3, 0xffff0000, v9
	v_add_f32_e32 v0, 1.0, v0
	v_rcp_f32_e32 v9, v0
	s_nop 0
	v_pk_mul_f32 v[4:5], v[8:9], v[4:5]
	s_nop 0
	v_pk_mul_f32 v[8:9], v[4:5], v[2:3]
	v_cvt_pk_bf16_f32 v2, v10, v11
	v_cvt_pk_bf16_f32 v3, v6, v7
	v_cvt_pk_bf16_f32 v4, v12, v13
	v_cvt_pk_bf16_f32 v5, v8, v9

.LBB0_695:
	v_max3_f32 v0, v66, v67, v68
	v_max3_f32 v116, v69, v70, v71
	v_max3_f32 v117, v72, v73, v74
	v_max3_f32 v0, v0, v75, v76
	v_max3_f32 v116, v116, v77, v78
	v_max3_f32 v117, v117, v79, v80
	v_max3_f32 v0, v0, v116, v117
	v_max_f32_e32 v0, v0, v81
	v_mov_b32_e32 v116, v0
	s_nop 1
	v_permlane32_swap_b32_e32 v116, v0
	s_nop 0
	v_max3_f32 v116, v115, v0, v116
	v_sub_f32_e32 v0, v115, v116
	v_exp_f32_e32 v0, v0
.LBB0_697:
	v_sub_f32_e32 v66, v66, v116
	v_exp_f32_e32 v115, v66
	v_sub_f32_e32 v67, v67, v116
	v_exp_f32_e32 v164, v67
	v_sub_f32_e32 v67, v68, v116
	v_exp_f32_e32 v165, v67
	v_sub_f32_e32 v67, v69, v116
	v_exp_f32_e32 v166, v67
	v_sub_f32_e32 v67, v70, v116
	v_add_f32_e32 v66, 0, v115
	v_exp_f32_e32 v167, v67
	v_sub_f32_e32 v67, v71, v116
	v_add_f32_e32 v66, v164, v66
	v_exp_f32_e32 v168, v67
	v_sub_f32_e32 v67, v72, v116
	v_add_f32_e32 v66, v165, v66
	v_exp_f32_e32 v169, v67
	v_sub_f32_e32 v67, v73, v116
	v_add_f32_e32 v66, v166, v66
	v_exp_f32_e32 v170, v67
	v_sub_f32_e32 v67, v74, v116
	v_add_f32_e32 v66, v167, v66
	v_exp_f32_e32 v171, v67
	v_sub_f32_e32 v67, v75, v116
	v_add_f32_e32 v66, v168, v66
	v_exp_f32_e32 v172, v67
	v_sub_f32_e32 v67, v76, v116
	v_add_f32_e32 v66, v169, v66
	v_exp_f32_e32 v173, v67
	v_sub_f32_e32 v67, v77, v116
	v_add_f32_e32 v66, v170, v66
	v_exp_f32_e32 v174, v67
	v_sub_f32_e32 v67, v78, v116
	v_add_f32_e32 v66, v171, v66
	v_exp_f32_e32 v175, v67
	v_sub_f32_e32 v67, v79, v116
	v_add_f32_e32 v66, v172, v66
	v_exp_f32_e32 v176, v67
	v_sub_f32_e32 v67, v80, v116
	v_add_f32_e32 v66, v173, v66
	v_exp_f32_e32 v177, v67
	v_sub_f32_e32 v67, v81, v116
	v_add_f32_e32 v66, v174, v66
	v_exp_f32_e32 v178, v67
	v_add_f32_e32 v66, v175, v66
	v_add_f32_e32 v66, v176, v66
	v_add_f32_e32 v66, v177, v66
	v_add_f32_e32 v179, v178, v66
	v_fmac_f32_e32 v179, v114, v0
	v_cvt_pk_bf16_f32 v164, v115, v164
	v_cvt_pk_bf16_f32 v165, v165, v166
	v_cvt_pk_bf16_f32 v166, v167, v168
	v_cvt_pk_bf16_f32 v167, v169, v170
	v_cvt_pk_bf16_f32 v140, v171, v172
	v_cvt_pk_bf16_f32 v141, v173, v174
	v_cvt_pk_bf16_f32 v142, v175, v176
	v_cvt_pk_bf16_f32 v143, v177, v178
	s_waitcnt lgkmcnt(8)
	v_pk_mul_f32 v[50:51], v[50:51], v[0:1] op_sel_hi:[1,0]
	v_pk_mul_f32 v[52:53], v[52:53], v[0:1] op_sel_hi:[1,0]
	v_pk_mul_f32 v[54:55], v[54:55], v[0:1] op_sel_hi:[1,0]
	v_pk_mul_f32 v[56:57], v[56:57], v[0:1] op_sel_hi:[1,0]
	v_pk_mul_f32 v[58:59], v[58:59], v[0:1] op_sel_hi:[1,0]
	v_pk_mul_f32 v[60:61], v[60:61], v[0:1] op_sel_hi:[1,0]
	v_pk_mul_f32 v[62:63], v[62:63], v[0:1] op_sel_hi:[1,0]
	v_pk_mul_f32 v[64:65], v[64:65], v[0:1] op_sel_hi:[1,0]
	v_pk_mul_f32 v[34:35], v[34:35], v[0:1] op_sel_hi:[1,0]
	v_pk_mul_f32 v[36:37], v[36:37], v[0:1] op_sel_hi:[1,0]
	v_mfma_f32_32x32x16_bf16 v[50:65], v[184:187], v[164:167], v[50:65]
	v_pk_mul_f32 v[38:39], v[38:39], v[0:1] op_sel_hi:[1,0]
	v_pk_mul_f32 v[40:41], v[40:41], v[0:1] op_sel_hi:[1,0]
	v_pk_mul_f32 v[42:43], v[42:43], v[0:1] op_sel_hi:[1,0]
	v_pk_mul_f32 v[44:45], v[44:45], v[0:1] op_sel_hi:[1,0]
	v_pk_mul_f32 v[46:47], v[46:47], v[0:1] op_sel_hi:[1,0]
	v_pk_mul_f32 v[48:49], v[48:49], v[0:1] op_sel_hi:[1,0]
	v_pk_mul_f32 v[18:19], v[18:19], v[0:1] op_sel_hi:[1,0]
	v_pk_mul_f32 v[20:21], v[20:21], v[0:1] op_sel_hi:[1,0]
	v_mfma_f32_32x32x16_bf16 v[34:49], v[188:191], v[164:167], v[34:49]
	v_pk_mul_f32 v[22:23], v[22:23], v[0:1] op_sel_hi:[1,0]
	v_pk_mul_f32 v[24:25], v[24:25], v[0:1] op_sel_hi:[1,0]
	v_pk_mul_f32 v[26:27], v[26:27], v[0:1] op_sel_hi:[1,0]
	v_pk_mul_f32 v[28:29], v[28:29], v[0:1] op_sel_hi:[1,0]
	v_pk_mul_f32 v[30:31], v[30:31], v[0:1] op_sel_hi:[1,0]
	v_pk_mul_f32 v[32:33], v[32:33], v[0:1] op_sel_hi:[1,0]
	v_pk_mul_f32 v[2:3], v[2:3], v[0:1] op_sel_hi:[1,0]
	v_pk_mul_f32 v[4:5], v[4:5], v[0:1] op_sel_hi:[1,0]
	v_mfma_f32_32x32x16_bf16 v[18:33], v[192:195], v[164:167], v[18:33]
	v_pk_mul_f32 v[6:7], v[6:7], v[0:1] op_sel_hi:[1,0]
	v_pk_mul_f32 v[8:9], v[8:9], v[0:1] op_sel_hi:[1,0]
	v_pk_mul_f32 v[10:11], v[10:11], v[0:1] op_sel_hi:[1,0]
	v_pk_mul_f32 v[12:13], v[12:13], v[0:1] op_sel_hi:[1,0]
	v_pk_mul_f32 v[14:15], v[14:15], v[0:1] op_sel_hi:[1,0]
	v_pk_mul_f32 v[16:17], v[16:17], v[0:1] op_sel_hi:[1,0]
	v_mov_b32_e32 v114, v179
	v_mov_b32_e32 v115, v116
	v_mfma_f32_32x32x16_bf16 v[2:17], v[196:199], v[164:167], v[2:17]
	s_waitcnt lgkmcnt(0)
	v_mfma_f32_32x32x16_bf16 v[50:65], v[200:203], v[140:143], v[50:65]
	v_mfma_f32_32x32x16_bf16 v[34:49], v[222:225], v[140:143], v[34:49]
	v_mfma_f32_32x32x16_bf16 v[18:33], v[226:229], v[140:143], v[18:33]
	v_mfma_f32_32x32x16_bf16 v[2:17], v[230:233], v[140:143], v[2:17]
